# short-conv gate phase rewritten by hand: a wave owns a strip of consecutive rows, each c|v row loaded and multiplied once, loads three rows ahead (replaces the tap-table patch of that phase)
# speedup vs baseline: 1.0016x; 1.0016x over previous
; __device__ __forceinline__ void convgate_phase(const bf16_t* U, bf16_t* H, int rows, const float* ck, int gw, int NGW, int lane) {
;     for (int row = gw; row < rows; row += NGW) {
;         const bool lat = row < ML; const int t = lat ? (row & (SEQ - 1)) : ((row - ML) & (CL - 1)); const int L = lat ? SEQ : CL;
;         const bool hasp = t > 0, hasn = t < L - 1;
;         const bf16_t* ur = U + (size_t)row * 3072;
;         u32x4 bq[2], cq[2], vq[2], cp[2], vp[2], cn[2], vn[2];
; #pragma unroll
;         for (int hf = 0; hf < 2; ++hf) {
;             const int c0 = lane * 16 + hf * 8;
;             bq[hf] = *(const u32x4*)(ur + c0); cq[hf] = *(const u32x4*)(ur + 1024 + c0); vq[hf] = *(const u32x4*)(ur + 2048 + c0);
;             cp[hf] = (u32x4){0, 0, 0, 0}; vp[hf] = cp[hf]; cn[hf] = cp[hf]; vn[hf] = cp[hf];
;             if (hasp) { cp[hf] = *(const u32x4*)(ur - 3072 + 1024 + c0); vp[hf] = *(const u32x4*)(ur - 3072 + 2048 + c0); }
;             if (hasn) { cn[hf] = *(const u32x4*)(ur + 3072 + 1024 + c0); vn[hf] = *(const u32x4*)(ur + 3072 + 2048 + c0); }
;         }
.LBB0_893:
	s_andn2_b64 vcc, exec, s[4:5]
	s_cbranch_vccnz .LBB0_906
	s_cmp_ge_i32 s16, s65
	v_mov_b32_e32 v0, v196
	s_cbranch_scc1 .LBB0_906
	s_load_dwordx2 s[0:1], s[62:63], 0x50
	s_lshl_b64 s[4:5], s[72:73], 12
	v_and_b32_e32 v3, 63, v196
	v_lshlrev_b32_e32 v1, 5, v3
	v_add_u32_e32 v2, 0x1000, v1
	v_lshlrev_b32_e32 v3, 6, v3
	s_lshr_b32 s10, s65, 11
	s_mul_i32 s11, s16, s10
	s_mov_b32 s14, 0xffff0000
	s_movk_i32 s3, 0x7ff
	s_movk_i32 s13, 0xff
	s_waitcnt lgkmcnt(0)
	s_add_u32 s0, s0, s4
	s_addc_u32 s1, s1, s5
	s_add_u32 s22, s0, 0x1000
	s_addc_u32 s23, s1, 0
	s_add_u32 s24, s0, 0x2000
	s_addc_u32 s25, s1, 0
	global_load_dwordx4 v[4:7], v3, s[0:1]
	global_load_dwordx4 v[8:11], v3, s[0:1] offset:16
	global_load_dwordx4 v[12:15], v3, s[0:1] offset:32
	global_load_dwordx4 v[16:19], v3, s[0:1] offset:48
	global_load_dwordx4 v[20:23], v3, s[22:23]
	global_load_dwordx4 v[24:27], v3, s[22:23] offset:16
	global_load_dwordx4 v[28:31], v3, s[22:23] offset:32
	global_load_dwordx4 v[32:35], v3, s[22:23] offset:48
	global_load_dwordx4 v[36:39], v3, s[24:25]
	global_load_dwordx4 v[40:43], v3, s[24:25] offset:16
	global_load_dwordx4 v[44:47], v3, s[24:25] offset:32
	global_load_dwordx4 v[48:51], v3, s[24:25] offset:48
	s_mul_i32 s12, s11, 0x1800
	s_add_u32 s6, s54, 0x9400000
	s_addc_u32 s7, s55, 0
	s_add_u32 s6, s6, s12
	s_addc_u32 s7, s7, 0
	s_sub_u32 s4, s6, 0x1800
	s_subb_u32 s5, s7, 0
	s_lshl_b32 s12, s11, 11
	s_add_u32 s8, s54, 0x7000000
	s_addc_u32 s9, s55, 0
	s_add_u32 s8, s8, s12
	s_addc_u32 s9, s9, 0
	s_cmp_eq_u32 s10, 9
	s_cbranch_scc0 .Lcg8_top
.Lcg9_top:
	global_load_dwordx4 v[114:117], v1, s[4:5] offset:2048
	global_load_dwordx4 v[118:121], v1, s[4:5] offset:2064
	global_load_dwordx4 v[122:125], v2, s[4:5]
	global_load_dwordx4 v[126:129], v2, s[4:5] offset:16
	s_add_u32 s4, s4, 0x1800
	s_addc_u32 s5, s5, 0
	global_load_dwordx4 v[130:133], v1, s[4:5] offset:2048
	global_load_dwordx4 v[134:137], v1, s[4:5] offset:2064
	global_load_dwordx4 v[138:141], v2, s[4:5]
	global_load_dwordx4 v[142:145], v2, s[4:5] offset:16
	s_add_u32 s4, s4, 0x1800
	s_addc_u32 s5, s5, 0
	global_load_dwordx4 v[146:149], v1, s[6:7]
	global_load_dwordx4 v[150:153], v1, s[6:7] offset:16
	s_add_u32 s6, s6, 0x1800
	s_addc_u32 s7, s7, 0
	global_load_dwordx4 v[160:163], v1, s[4:5] offset:2048
	global_load_dwordx4 v[164:167], v1, s[4:5] offset:2064
	global_load_dwordx4 v[168:171], v2, s[4:5]
	global_load_dwordx4 v[172:175], v2, s[4:5] offset:16
	s_add_u32 s4, s4, 0x1800
	s_addc_u32 s5, s5, 0
	global_load_dwordx4 v[176:179], v1, s[6:7]
	global_load_dwordx4 v[180:183], v1, s[6:7] offset:16
	s_add_u32 s6, s6, 0x1800
	s_addc_u32 s7, s7, 0
	s_waitcnt vmcnt(12)
	v_lshlrev_b32_e32 v202, 16, v114
	v_and_b32_e32 v203, s14, v114
	v_lshlrev_b32_e32 v204, 16, v122
	v_and_b32_e32 v205, s14, v122
	v_pk_mul_f32 v[52:53], v[202:203], v[204:205]
	v_lshlrev_b32_e32 v206, 16, v115
	v_and_b32_e32 v207, s14, v115
	v_lshlrev_b32_e32 v208, 16, v123
	v_and_b32_e32 v209, s14, v123
	v_pk_mul_f32 v[54:55], v[206:207], v[208:209]
	v_lshlrev_b32_e32 v210, 16, v116
	v_and_b32_e32 v211, s14, v116
	v_lshlrev_b32_e32 v212, 16, v124
	v_and_b32_e32 v213, s14, v124
	v_pk_mul_f32 v[56:57], v[210:211], v[212:213]
	v_lshlrev_b32_e32 v202, 16, v117
	v_and_b32_e32 v203, s14, v117
	v_lshlrev_b32_e32 v204, 16, v125
	v_and_b32_e32 v205, s14, v125
	v_pk_mul_f32 v[58:59], v[202:203], v[204:205]
	v_lshlrev_b32_e32 v206, 16, v118
	v_and_b32_e32 v207, s14, v118
	v_lshlrev_b32_e32 v208, 16, v126
	v_and_b32_e32 v209, s14, v126
	v_pk_mul_f32 v[60:61], v[206:207], v[208:209]
	v_lshlrev_b32_e32 v210, 16, v119
	v_and_b32_e32 v211, s14, v119
	v_lshlrev_b32_e32 v212, 16, v127
	v_and_b32_e32 v213, s14, v127
	v_pk_mul_f32 v[62:63], v[210:211], v[212:213]
	v_lshlrev_b32_e32 v202, 16, v120
	v_and_b32_e32 v203, s14, v120
	v_lshlrev_b32_e32 v204, 16, v128
	v_and_b32_e32 v205, s14, v128
	v_pk_mul_f32 v[64:65], v[202:203], v[204:205]
	v_lshlrev_b32_e32 v206, 16, v121
	v_and_b32_e32 v207, s14, v121
	v_lshlrev_b32_e32 v208, 16, v129
	v_and_b32_e32 v209, s14, v129
	v_pk_mul_f32 v[66:67], v[206:207], v[208:209]
	global_load_dwordx4 v[114:117], v1, s[4:5] offset:2048
	global_load_dwordx4 v[118:121], v1, s[4:5] offset:2064
	global_load_dwordx4 v[122:125], v2, s[4:5]
	global_load_dwordx4 v[126:129], v2, s[4:5] offset:16
	s_add_u32 s4, s4, 0x1800
	s_addc_u32 s5, s5, 0
	global_load_dwordx4 v[226:229], v1, s[6:7]
	global_load_dwordx4 v[230:233], v1, s[6:7] offset:16
	s_add_u32 s6, s6, 0x1800
	s_addc_u32 s7, s7, 0
	s_waitcnt vmcnt(14)
	v_lshlrev_b32_e32 v202, 16, v130
	v_and_b32_e32 v203, s14, v130
	v_lshlrev_b32_e32 v204, 16, v138
	v_and_b32_e32 v205, s14, v138
	v_pk_mul_f32 v[68:69], v[202:203], v[204:205]
	v_lshlrev_b32_e32 v206, 16, v131
	v_and_b32_e32 v207, s14, v131
	v_lshlrev_b32_e32 v208, 16, v139
	v_and_b32_e32 v209, s14, v139
	v_pk_mul_f32 v[70:71], v[206:207], v[208:209]
	v_lshlrev_b32_e32 v210, 16, v132
	v_and_b32_e32 v211, s14, v132
	v_lshlrev_b32_e32 v212, 16, v140
	v_and_b32_e32 v213, s14, v140
	v_pk_mul_f32 v[72:73], v[210:211], v[212:213]
	v_lshlrev_b32_e32 v202, 16, v133
	v_and_b32_e32 v203, s14, v133
	v_lshlrev_b32_e32 v204, 16, v141
	v_and_b32_e32 v205, s14, v141
	v_pk_mul_f32 v[74:75], v[202:203], v[204:205]
	v_lshlrev_b32_e32 v206, 16, v134
	v_and_b32_e32 v207, s14, v134
	v_lshlrev_b32_e32 v208, 16, v142
	v_and_b32_e32 v209, s14, v142
	v_pk_mul_f32 v[76:77], v[206:207], v[208:209]
	v_lshlrev_b32_e32 v210, 16, v135
	v_and_b32_e32 v211, s14, v135
	v_lshlrev_b32_e32 v212, 16, v143
	v_and_b32_e32 v213, s14, v143
	v_pk_mul_f32 v[78:79], v[210:211], v[212:213]
	v_lshlrev_b32_e32 v202, 16, v136
	v_and_b32_e32 v203, s14, v136
	v_lshlrev_b32_e32 v204, 16, v144
	v_and_b32_e32 v205, s14, v144
	v_pk_mul_f32 v[80:81], v[202:203], v[204:205]
	v_lshlrev_b32_e32 v206, 16, v137
	v_and_b32_e32 v207, s14, v137
	v_lshlrev_b32_e32 v208, 16, v145
	v_and_b32_e32 v209, s14, v145
	v_pk_mul_f32 v[82:83], v[206:207], v[208:209]
	global_load_dwordx4 v[130:133], v1, s[4:5] offset:2048
	global_load_dwordx4 v[134:137], v1, s[4:5] offset:2064
	global_load_dwordx4 v[138:141], v2, s[4:5]
	global_load_dwordx4 v[142:145], v2, s[4:5] offset:16
	s_add_u32 s4, s4, 0x1800
	s_addc_u32 s5, s5, 0
	s_waitcnt vmcnt(12)
; __device__ __forceinline__ unsigned cvt_pk_bf16(float lo, float hi) { unsigned r; asm volatile("v_cvt_pk_bf16_f32 %0, %1, %2" : "=v"(r) : "v"(lo), "v"(hi)); return r; }
; __device__ __forceinline__ float bflo(unsigned w) { return __uint_as_float(w << 16); }
; __device__ __forceinline__ float bfhi(unsigned w) { return __uint_as_float(w & 0xffff0000u); }
; __device__ __forceinline__ void convgate_phase(const bf16_t* U, bf16_t* H, int rows, const float* ck, int gw, int NGW, int lane) {
;     ...
; #pragma unroll
;         for (int hf = 0; hf < 2; ++hf) {
;             const int c0 = lane * 16 + hf * 8;
;             u32x4 ow;
; #pragma unroll
;             for (int e = 0; e < 4; ++e) {
;                 const f32x2 w0 = *(const f32x2*)(ck + c0 + 2 * e), w1 = *(const f32x2*)(ck + D + c0 + 2 * e), w2 = *(const f32x2*)(ck + 2 * D + c0 + 2 * e);
;                 const float lo = bflo(bq[hf][e]) * (w0[0] * (bflo(cp[hf][e]) * bflo(vp[hf][e])) + w1[0] * (bflo(cq[hf][e]) * bflo(vq[hf][e])) + w2[0] * (bflo(cn[hf][e]) * bflo(vn[hf][e])));
;                 const float hi = bfhi(bq[hf][e]) * (w0[1] * (bfhi(cp[hf][e]) * bfhi(vp[hf][e])) + w1[1] * (bfhi(cq[hf][e]) * bfhi(vq[hf][e])) + w2[1] * (bfhi(cn[hf][e]) * bfhi(vn[hf][e])));
;                 ow[e] = cvt_pk_bf16(lo, hi);
;             }
;             *(u32x4*)(H + (size_t)row * D + c0) = ow;
;         }
	v_lshlrev_b32_e32 v202, 16, v160
	v_and_b32_e32 v203, s14, v160
	v_lshlrev_b32_e32 v204, 16, v168
	v_and_b32_e32 v205, s14, v168
	v_pk_mul_f32 v[98:99], v[202:203], v[204:205]
	v_lshlrev_b32_e32 v206, 16, v161
	v_and_b32_e32 v207, s14, v161
	v_lshlrev_b32_e32 v208, 16, v169
	v_and_b32_e32 v209, s14, v169
	v_pk_mul_f32 v[100:101], v[206:207], v[208:209]
	v_lshlrev_b32_e32 v210, 16, v162
	v_and_b32_e32 v211, s14, v162
	v_lshlrev_b32_e32 v212, 16, v170
	v_and_b32_e32 v213, s14, v170
	v_pk_mul_f32 v[102:103], v[210:211], v[212:213]
	v_lshlrev_b32_e32 v202, 16, v163
	v_and_b32_e32 v203, s14, v163
	v_lshlrev_b32_e32 v204, 16, v171
	v_and_b32_e32 v205, s14, v171
	v_pk_mul_f32 v[104:105], v[202:203], v[204:205]
	v_lshlrev_b32_e32 v206, 16, v164
	v_and_b32_e32 v207, s14, v164
	v_lshlrev_b32_e32 v208, 16, v172
	v_and_b32_e32 v209, s14, v172
	v_pk_mul_f32 v[106:107], v[206:207], v[208:209]
	v_lshlrev_b32_e32 v210, 16, v165
	v_and_b32_e32 v211, s14, v165
	v_lshlrev_b32_e32 v212, 16, v173
	v_and_b32_e32 v213, s14, v173
	v_pk_mul_f32 v[108:109], v[210:211], v[212:213]
	v_lshlrev_b32_e32 v202, 16, v166
	v_and_b32_e32 v203, s14, v166
	v_lshlrev_b32_e32 v204, 16, v174
	v_and_b32_e32 v205, s14, v174
	v_pk_mul_f32 v[110:111], v[202:203], v[204:205]
	v_lshlrev_b32_e32 v206, 16, v167
	v_and_b32_e32 v207, s14, v167
	v_lshlrev_b32_e32 v208, 16, v175
	v_and_b32_e32 v209, s14, v175
	v_pk_mul_f32 v[112:113], v[206:207], v[208:209]
	global_load_dwordx4 v[160:163], v1, s[4:5] offset:2048
	global_load_dwordx4 v[164:167], v1, s[4:5] offset:2064
	global_load_dwordx4 v[168:171], v2, s[4:5]
	global_load_dwordx4 v[172:175], v2, s[4:5] offset:16
	s_add_u32 s4, s4, 0x1800
	s_addc_u32 s5, s5, 0
	s_add_i32 s12, s11, 0
	s_cmp_lt_u32 s12, 0x4000
	s_cselect_b32 s29, s3, s13
	s_and_b32 s27, s12, s29
	v_pk_mul_f32 v[234:235], v[20:21], v[68:69]
	v_pk_mul_f32 v[236:237], v[22:23], v[70:71]
	v_pk_mul_f32 v[238:239], v[24:25], v[72:73]
	v_pk_mul_f32 v[240:241], v[26:27], v[74:75]
	v_pk_mul_f32 v[242:243], v[28:29], v[76:77]
	v_pk_mul_f32 v[244:245], v[30:31], v[78:79]
	v_pk_mul_f32 v[246:247], v[32:33], v[80:81]
	v_pk_mul_f32 v[248:249], v[34:35], v[82:83]
	s_cmp_eq_u32 s27, 0
	s_cbranch_scc1 .Lcg9_np0
	v_pk_fma_f32 v[234:235], v[4:5], v[52:53], v[234:235]
	v_pk_fma_f32 v[236:237], v[6:7], v[54:55], v[236:237]
	v_pk_fma_f32 v[238:239], v[8:9], v[56:57], v[238:239]
	v_pk_fma_f32 v[240:241], v[10:11], v[58:59], v[240:241]
	v_pk_fma_f32 v[242:243], v[12:13], v[60:61], v[242:243]
	v_pk_fma_f32 v[244:245], v[14:15], v[62:63], v[244:245]
	v_pk_fma_f32 v[246:247], v[16:17], v[64:65], v[246:247]
	v_pk_fma_f32 v[248:249], v[18:19], v[66:67], v[248:249]
.Lcg9_np0:
	s_cmp_eq_u32 s27, s29
	s_cbranch_scc1 .Lcg9_nn0
	v_pk_fma_f32 v[234:235], v[36:37], v[98:99], v[234:235]
	v_pk_fma_f32 v[236:237], v[38:39], v[100:101], v[236:237]
	v_pk_fma_f32 v[238:239], v[40:41], v[102:103], v[238:239]
	v_pk_fma_f32 v[240:241], v[42:43], v[104:105], v[240:241]
	v_pk_fma_f32 v[242:243], v[44:45], v[106:107], v[242:243]
	v_pk_fma_f32 v[244:245], v[46:47], v[108:109], v[244:245]
	v_pk_fma_f32 v[246:247], v[48:49], v[110:111], v[246:247]
	v_pk_fma_f32 v[248:249], v[50:51], v[112:113], v[248:249]
.Lcg9_nn0:
	v_lshlrev_b32_e32 v202, 16, v146
	v_and_b32_e32 v203, s14, v146
	v_pk_mul_f32 v[234:235], v[234:235], v[202:203]
	v_lshlrev_b32_e32 v206, 16, v147
	v_and_b32_e32 v207, s14, v147
	v_pk_mul_f32 v[236:237], v[236:237], v[206:207]
	v_lshlrev_b32_e32 v210, 16, v148
	v_and_b32_e32 v211, s14, v148
	v_pk_mul_f32 v[238:239], v[238:239], v[210:211]
	v_lshlrev_b32_e32 v202, 16, v149
	v_and_b32_e32 v203, s14, v149
	v_pk_mul_f32 v[240:241], v[240:241], v[202:203]
	v_lshlrev_b32_e32 v206, 16, v150
	v_and_b32_e32 v207, s14, v150
	v_pk_mul_f32 v[242:243], v[242:243], v[206:207]
	v_lshlrev_b32_e32 v210, 16, v151
	v_and_b32_e32 v211, s14, v151
	v_pk_mul_f32 v[244:245], v[244:245], v[210:211]
	v_lshlrev_b32_e32 v202, 16, v152
	v_and_b32_e32 v203, s14, v152
	v_pk_mul_f32 v[246:247], v[246:247], v[202:203]
	v_lshlrev_b32_e32 v206, 16, v153
	v_and_b32_e32 v207, s14, v153
	v_pk_mul_f32 v[248:249], v[248:249], v[206:207]
	v_cvt_pk_bf16_f32 v84, v234, v235
	v_cvt_pk_bf16_f32 v85, v236, v237
	v_cvt_pk_bf16_f32 v86, v238, v239
	v_cvt_pk_bf16_f32 v87, v240, v241
	v_cvt_pk_bf16_f32 v88, v242, v243
	v_cvt_pk_bf16_f32 v89, v244, v245
	v_cvt_pk_bf16_f32 v90, v246, v247
	v_cvt_pk_bf16_f32 v91, v248, v249
	global_store_dwordx4 v1, v[84:87], s[8:9]
	global_store_dwordx4 v1, v[88:91], s[8:9] offset:16
	s_add_u32 s8, s8, 0x800
	s_addc_u32 s9, s9, 0
	global_load_dwordx4 v[146:149], v1, s[6:7]
	global_load_dwordx4 v[150:153], v1, s[6:7] offset:16
	s_add_u32 s6, s6, 0x1800
	s_addc_u32 s7, s7, 0
	s_waitcnt vmcnt(14)
	v_lshlrev_b32_e32 v202, 16, v114
	v_and_b32_e32 v203, s14, v114
	v_lshlrev_b32_e32 v204, 16, v122
	v_and_b32_e32 v205, s14, v122
	v_pk_mul_f32 v[52:53], v[202:203], v[204:205]
	v_lshlrev_b32_e32 v206, 16, v115
	v_and_b32_e32 v207, s14, v115
	v_lshlrev_b32_e32 v208, 16, v123
	v_and_b32_e32 v209, s14, v123
	v_pk_mul_f32 v[54:55], v[206:207], v[208:209]
	v_lshlrev_b32_e32 v210, 16, v116
	v_and_b32_e32 v211, s14, v116
	v_lshlrev_b32_e32 v212, 16, v124
	v_and_b32_e32 v213, s14, v124
	v_pk_mul_f32 v[56:57], v[210:211], v[212:213]
	v_lshlrev_b32_e32 v202, 16, v117
	v_and_b32_e32 v203, s14, v117
	v_lshlrev_b32_e32 v204, 16, v125
	v_and_b32_e32 v205, s14, v125
	v_pk_mul_f32 v[58:59], v[202:203], v[204:205]
	v_lshlrev_b32_e32 v206, 16, v118
	v_and_b32_e32 v207, s14, v118
	v_lshlrev_b32_e32 v208, 16, v126
	v_and_b32_e32 v209, s14, v126
	v_pk_mul_f32 v[60:61], v[206:207], v[208:209]
	v_lshlrev_b32_e32 v210, 16, v119
	v_and_b32_e32 v211, s14, v119
	v_lshlrev_b32_e32 v212, 16, v127
	v_and_b32_e32 v213, s14, v127
	v_pk_mul_f32 v[62:63], v[210:211], v[212:213]
	v_lshlrev_b32_e32 v202, 16, v120
	v_and_b32_e32 v203, s14, v120
	v_lshlrev_b32_e32 v204, 16, v128
	v_and_b32_e32 v205, s14, v128
	v_pk_mul_f32 v[64:65], v[202:203], v[204:205]
	v_lshlrev_b32_e32 v206, 16, v121
	v_and_b32_e32 v207, s14, v121
	v_lshlrev_b32_e32 v208, 16, v129
	v_and_b32_e32 v209, s14, v129
	v_pk_mul_f32 v[66:67], v[206:207], v[208:209]
	global_load_dwordx4 v[114:117], v1, s[4:5] offset:2048
	global_load_dwordx4 v[118:121], v1, s[4:5] offset:2064
	global_load_dwordx4 v[122:125], v2, s[4:5]
	global_load_dwordx4 v[126:129], v2, s[4:5] offset:16
	s_add_u32 s4, s4, 0x1800
	s_addc_u32 s5, s5, 0
	s_add_i32 s12, s11, 1
	s_cmp_lt_u32 s12, 0x4000
	s_cselect_b32 s29, s3, s13
	s_and_b32 s27, s12, s29
	v_pk_mul_f32 v[234:235], v[20:21], v[98:99]
	v_pk_mul_f32 v[236:237], v[22:23], v[100:101]
	v_pk_mul_f32 v[238:239], v[24:25], v[102:103]
	v_pk_mul_f32 v[240:241], v[26:27], v[104:105]
	v_pk_mul_f32 v[242:243], v[28:29], v[106:107]
	v_pk_mul_f32 v[244:245], v[30:31], v[108:109]
	v_pk_mul_f32 v[246:247], v[32:33], v[110:111]
	v_pk_mul_f32 v[248:249], v[34:35], v[112:113]
	s_cmp_eq_u32 s27, 0
	s_cbranch_scc1 .Lcg9_np1
; __device__ __forceinline__ unsigned cvt_pk_bf16(float lo, float hi) { unsigned r; asm volatile("v_cvt_pk_bf16_f32 %0, %1, %2" : "=v"(r) : "v"(lo), "v"(hi)); return r; }
; __device__ __forceinline__ float bflo(unsigned w) { return __uint_as_float(w << 16); }
; __device__ __forceinline__ float bfhi(unsigned w) { return __uint_as_float(w & 0xffff0000u); }
; __device__ __forceinline__ void convgate_phase(const bf16_t* U, bf16_t* H, int rows, const float* ck, int gw, int NGW, int lane) {
;     ...
; #pragma unroll
;         for (int hf = 0; hf < 2; ++hf) {
;             const int c0 = lane * 16 + hf * 8;
;             u32x4 ow;
; #pragma unroll
;             for (int e = 0; e < 4; ++e) {
;                 const f32x2 w0 = *(const f32x2*)(ck + c0 + 2 * e), w1 = *(const f32x2*)(ck + D + c0 + 2 * e), w2 = *(const f32x2*)(ck + 2 * D + c0 + 2 * e);
;                 const float lo = bflo(bq[hf][e]) * (w0[0] * (bflo(cp[hf][e]) * bflo(vp[hf][e])) + w1[0] * (bflo(cq[hf][e]) * bflo(vq[hf][e])) + w2[0] * (bflo(cn[hf][e]) * bflo(vn[hf][e])));
;                 const float hi = bfhi(bq[hf][e]) * (w0[1] * (bfhi(cp[hf][e]) * bfhi(vp[hf][e])) + w1[1] * (bfhi(cq[hf][e]) * bfhi(vq[hf][e])) + w2[1] * (bfhi(cn[hf][e]) * bfhi(vn[hf][e])));
;                 ow[e] = cvt_pk_bf16(lo, hi);
;             }
;             *(u32x4*)(H + (size_t)row * D + c0) = ow;
;         }
	v_pk_fma_f32 v[234:235], v[4:5], v[68:69], v[234:235]
	v_pk_fma_f32 v[236:237], v[6:7], v[70:71], v[236:237]
	v_pk_fma_f32 v[238:239], v[8:9], v[72:73], v[238:239]
	v_pk_fma_f32 v[240:241], v[10:11], v[74:75], v[240:241]
	v_pk_fma_f32 v[242:243], v[12:13], v[76:77], v[242:243]
	v_pk_fma_f32 v[244:245], v[14:15], v[78:79], v[244:245]
	v_pk_fma_f32 v[246:247], v[16:17], v[80:81], v[246:247]
	v_pk_fma_f32 v[248:249], v[18:19], v[82:83], v[248:249]
.Lcg9_np1:
	s_cmp_eq_u32 s27, s29
	s_cbranch_scc1 .Lcg9_nn1
	v_pk_fma_f32 v[234:235], v[36:37], v[52:53], v[234:235]
	v_pk_fma_f32 v[236:237], v[38:39], v[54:55], v[236:237]
	v_pk_fma_f32 v[238:239], v[40:41], v[56:57], v[238:239]
	v_pk_fma_f32 v[240:241], v[42:43], v[58:59], v[240:241]
	v_pk_fma_f32 v[242:243], v[44:45], v[60:61], v[242:243]
	v_pk_fma_f32 v[244:245], v[46:47], v[62:63], v[244:245]
	v_pk_fma_f32 v[246:247], v[48:49], v[64:65], v[246:247]
	v_pk_fma_f32 v[248:249], v[50:51], v[66:67], v[248:249]
.Lcg9_nn1:
	v_lshlrev_b32_e32 v202, 16, v176
	v_and_b32_e32 v203, s14, v176
	v_pk_mul_f32 v[234:235], v[234:235], v[202:203]
	v_lshlrev_b32_e32 v206, 16, v177
	v_and_b32_e32 v207, s14, v177
	v_pk_mul_f32 v[236:237], v[236:237], v[206:207]
	v_lshlrev_b32_e32 v210, 16, v178
	v_and_b32_e32 v211, s14, v178
	v_pk_mul_f32 v[238:239], v[238:239], v[210:211]
	v_lshlrev_b32_e32 v202, 16, v179
	v_and_b32_e32 v203, s14, v179
	v_pk_mul_f32 v[240:241], v[240:241], v[202:203]
	v_lshlrev_b32_e32 v206, 16, v180
	v_and_b32_e32 v207, s14, v180
	v_pk_mul_f32 v[242:243], v[242:243], v[206:207]
	v_lshlrev_b32_e32 v210, 16, v181
	v_and_b32_e32 v211, s14, v181
	v_pk_mul_f32 v[244:245], v[244:245], v[210:211]
	v_lshlrev_b32_e32 v202, 16, v182
	v_and_b32_e32 v203, s14, v182
	v_pk_mul_f32 v[246:247], v[246:247], v[202:203]
	v_lshlrev_b32_e32 v206, 16, v183
	v_and_b32_e32 v207, s14, v183
	v_pk_mul_f32 v[248:249], v[248:249], v[206:207]
	v_cvt_pk_bf16_f32 v84, v234, v235
	v_cvt_pk_bf16_f32 v85, v236, v237
	v_cvt_pk_bf16_f32 v86, v238, v239
	v_cvt_pk_bf16_f32 v87, v240, v241
	v_cvt_pk_bf16_f32 v88, v242, v243
	v_cvt_pk_bf16_f32 v89, v244, v245
	v_cvt_pk_bf16_f32 v90, v246, v247
	v_cvt_pk_bf16_f32 v91, v248, v249
	global_store_dwordx4 v1, v[84:87], s[8:9]
	global_store_dwordx4 v1, v[88:91], s[8:9] offset:16
	s_add_u32 s8, s8, 0x800
	s_addc_u32 s9, s9, 0
	global_load_dwordx4 v[176:179], v1, s[6:7]
	global_load_dwordx4 v[180:183], v1, s[6:7] offset:16
	s_add_u32 s6, s6, 0x1800
	s_addc_u32 s7, s7, 0
	s_waitcnt vmcnt(16)
	v_lshlrev_b32_e32 v202, 16, v130
	v_and_b32_e32 v203, s14, v130
	v_lshlrev_b32_e32 v204, 16, v138
	v_and_b32_e32 v205, s14, v138
	v_pk_mul_f32 v[68:69], v[202:203], v[204:205]
	v_lshlrev_b32_e32 v206, 16, v131
	v_and_b32_e32 v207, s14, v131
	v_lshlrev_b32_e32 v208, 16, v139
	v_and_b32_e32 v209, s14, v139
	v_pk_mul_f32 v[70:71], v[206:207], v[208:209]
	v_lshlrev_b32_e32 v210, 16, v132
	v_and_b32_e32 v211, s14, v132
	v_lshlrev_b32_e32 v212, 16, v140
	v_and_b32_e32 v213, s14, v140
	v_pk_mul_f32 v[72:73], v[210:211], v[212:213]
	v_lshlrev_b32_e32 v202, 16, v133
	v_and_b32_e32 v203, s14, v133
	v_lshlrev_b32_e32 v204, 16, v141
	v_and_b32_e32 v205, s14, v141
	v_pk_mul_f32 v[74:75], v[202:203], v[204:205]
	v_lshlrev_b32_e32 v206, 16, v134
	v_and_b32_e32 v207, s14, v134
	v_lshlrev_b32_e32 v208, 16, v142
	v_and_b32_e32 v209, s14, v142
	v_pk_mul_f32 v[76:77], v[206:207], v[208:209]
	v_lshlrev_b32_e32 v210, 16, v135
	v_and_b32_e32 v211, s14, v135
	v_lshlrev_b32_e32 v212, 16, v143
	v_and_b32_e32 v213, s14, v143
	v_pk_mul_f32 v[78:79], v[210:211], v[212:213]
	v_lshlrev_b32_e32 v202, 16, v136
	v_and_b32_e32 v203, s14, v136
	v_lshlrev_b32_e32 v204, 16, v144
	v_and_b32_e32 v205, s14, v144
	v_pk_mul_f32 v[80:81], v[202:203], v[204:205]
	v_lshlrev_b32_e32 v206, 16, v137
	v_and_b32_e32 v207, s14, v137
	v_lshlrev_b32_e32 v208, 16, v145
	v_and_b32_e32 v209, s14, v145
	v_pk_mul_f32 v[82:83], v[206:207], v[208:209]
	global_load_dwordx4 v[130:133], v1, s[4:5] offset:2048
	global_load_dwordx4 v[134:137], v1, s[4:5] offset:2064
	global_load_dwordx4 v[138:141], v2, s[4:5]
	global_load_dwordx4 v[142:145], v2, s[4:5] offset:16
	s_add_u32 s4, s4, 0x1800
	s_addc_u32 s5, s5, 0
	s_add_i32 s12, s11, 2
	s_cmp_lt_u32 s12, 0x4000
	s_cselect_b32 s29, s3, s13
	s_and_b32 s27, s12, s29
	v_pk_mul_f32 v[234:235], v[20:21], v[52:53]
	v_pk_mul_f32 v[236:237], v[22:23], v[54:55]
	v_pk_mul_f32 v[238:239], v[24:25], v[56:57]
	v_pk_mul_f32 v[240:241], v[26:27], v[58:59]
	v_pk_mul_f32 v[242:243], v[28:29], v[60:61]
	v_pk_mul_f32 v[244:245], v[30:31], v[62:63]
	v_pk_mul_f32 v[246:247], v[32:33], v[64:65]
	v_pk_mul_f32 v[248:249], v[34:35], v[66:67]
	s_cmp_eq_u32 s27, 0
	s_cbranch_scc1 .Lcg9_np2
	v_pk_fma_f32 v[234:235], v[4:5], v[98:99], v[234:235]
	v_pk_fma_f32 v[236:237], v[6:7], v[100:101], v[236:237]
	v_pk_fma_f32 v[238:239], v[8:9], v[102:103], v[238:239]
	v_pk_fma_f32 v[240:241], v[10:11], v[104:105], v[240:241]
	v_pk_fma_f32 v[242:243], v[12:13], v[106:107], v[242:243]
	v_pk_fma_f32 v[244:245], v[14:15], v[108:109], v[244:245]
	v_pk_fma_f32 v[246:247], v[16:17], v[110:111], v[246:247]
	v_pk_fma_f32 v[248:249], v[18:19], v[112:113], v[248:249]
; __device__ __forceinline__ unsigned cvt_pk_bf16(float lo, float hi) { unsigned r; asm volatile("v_cvt_pk_bf16_f32 %0, %1, %2" : "=v"(r) : "v"(lo), "v"(hi)); return r; }
; __device__ __forceinline__ float bflo(unsigned w) { return __uint_as_float(w << 16); }
; __device__ __forceinline__ float bfhi(unsigned w) { return __uint_as_float(w & 0xffff0000u); }
; __device__ __forceinline__ void convgate_phase(const bf16_t* U, bf16_t* H, int rows, const float* ck, int gw, int NGW, int lane) {
;     ...
; #pragma unroll
;         for (int hf = 0; hf < 2; ++hf) {
;             const int c0 = lane * 16 + hf * 8;
;             u32x4 ow;
; #pragma unroll
;             for (int e = 0; e < 4; ++e) {
;                 const f32x2 w0 = *(const f32x2*)(ck + c0 + 2 * e), w1 = *(const f32x2*)(ck + D + c0 + 2 * e), w2 = *(const f32x2*)(ck + 2 * D + c0 + 2 * e);
;                 const float lo = bflo(bq[hf][e]) * (w0[0] * (bflo(cp[hf][e]) * bflo(vp[hf][e])) + w1[0] * (bflo(cq[hf][e]) * bflo(vq[hf][e])) + w2[0] * (bflo(cn[hf][e]) * bflo(vn[hf][e])));
;                 const float hi = bfhi(bq[hf][e]) * (w0[1] * (bfhi(cp[hf][e]) * bfhi(vp[hf][e])) + w1[1] * (bfhi(cq[hf][e]) * bfhi(vq[hf][e])) + w2[1] * (bfhi(cn[hf][e]) * bfhi(vn[hf][e])));
;                 ow[e] = cvt_pk_bf16(lo, hi);
;             }
;             *(u32x4*)(H + (size_t)row * D + c0) = ow;
;         }
.Lcg9_np2:
	s_cmp_eq_u32 s27, s29
	s_cbranch_scc1 .Lcg9_nn2
	v_pk_fma_f32 v[234:235], v[36:37], v[68:69], v[234:235]
	v_pk_fma_f32 v[236:237], v[38:39], v[70:71], v[236:237]
	v_pk_fma_f32 v[238:239], v[40:41], v[72:73], v[238:239]
	v_pk_fma_f32 v[240:241], v[42:43], v[74:75], v[240:241]
	v_pk_fma_f32 v[242:243], v[44:45], v[76:77], v[242:243]
	v_pk_fma_f32 v[244:245], v[46:47], v[78:79], v[244:245]
	v_pk_fma_f32 v[246:247], v[48:49], v[80:81], v[246:247]
	v_pk_fma_f32 v[248:249], v[50:51], v[82:83], v[248:249]
.Lcg9_nn2:
	v_lshlrev_b32_e32 v202, 16, v226
	v_and_b32_e32 v203, s14, v226
	v_pk_mul_f32 v[234:235], v[234:235], v[202:203]
	v_lshlrev_b32_e32 v206, 16, v227
	v_and_b32_e32 v207, s14, v227
	v_pk_mul_f32 v[236:237], v[236:237], v[206:207]
	v_lshlrev_b32_e32 v210, 16, v228
	v_and_b32_e32 v211, s14, v228
	v_pk_mul_f32 v[238:239], v[238:239], v[210:211]
	v_lshlrev_b32_e32 v202, 16, v229
	v_and_b32_e32 v203, s14, v229
	v_pk_mul_f32 v[240:241], v[240:241], v[202:203]
	v_lshlrev_b32_e32 v206, 16, v230
	v_and_b32_e32 v207, s14, v230
	v_pk_mul_f32 v[242:243], v[242:243], v[206:207]
	v_lshlrev_b32_e32 v210, 16, v231
	v_and_b32_e32 v211, s14, v231
	v_pk_mul_f32 v[244:245], v[244:245], v[210:211]
	v_lshlrev_b32_e32 v202, 16, v232
	v_and_b32_e32 v203, s14, v232
	v_pk_mul_f32 v[246:247], v[246:247], v[202:203]
	v_lshlrev_b32_e32 v206, 16, v233
	v_and_b32_e32 v207, s14, v233
	v_pk_mul_f32 v[248:249], v[248:249], v[206:207]
	v_cvt_pk_bf16_f32 v84, v234, v235
	v_cvt_pk_bf16_f32 v85, v236, v237
	v_cvt_pk_bf16_f32 v86, v238, v239
	v_cvt_pk_bf16_f32 v87, v240, v241
	v_cvt_pk_bf16_f32 v88, v242, v243
	v_cvt_pk_bf16_f32 v89, v244, v245
	v_cvt_pk_bf16_f32 v90, v246, v247
	v_cvt_pk_bf16_f32 v91, v248, v249
	global_store_dwordx4 v1, v[84:87], s[8:9]
	global_store_dwordx4 v1, v[88:91], s[8:9] offset:16
	s_add_u32 s8, s8, 0x800
	s_addc_u32 s9, s9, 0
	global_load_dwordx4 v[226:229], v1, s[6:7]
	global_load_dwordx4 v[230:233], v1, s[6:7] offset:16
	s_add_u32 s6, s6, 0x1800
	s_addc_u32 s7, s7, 0
	s_waitcnt vmcnt(16)
	v_lshlrev_b32_e32 v202, 16, v160
	v_and_b32_e32 v203, s14, v160
	v_lshlrev_b32_e32 v204, 16, v168
	v_and_b32_e32 v205, s14, v168
	v_pk_mul_f32 v[98:99], v[202:203], v[204:205]
	v_lshlrev_b32_e32 v206, 16, v161
	v_and_b32_e32 v207, s14, v161
	v_lshlrev_b32_e32 v208, 16, v169
	v_and_b32_e32 v209, s14, v169
	v_pk_mul_f32 v[100:101], v[206:207], v[208:209]
	v_lshlrev_b32_e32 v210, 16, v162
	v_and_b32_e32 v211, s14, v162
	v_lshlrev_b32_e32 v212, 16, v170
	v_and_b32_e32 v213, s14, v170
	v_pk_mul_f32 v[102:103], v[210:211], v[212:213]
	v_lshlrev_b32_e32 v202, 16, v163
	v_and_b32_e32 v203, s14, v163
	v_lshlrev_b32_e32 v204, 16, v171
	v_and_b32_e32 v205, s14, v171
	v_pk_mul_f32 v[104:105], v[202:203], v[204:205]
	v_lshlrev_b32_e32 v206, 16, v164
	v_and_b32_e32 v207, s14, v164
	v_lshlrev_b32_e32 v208, 16, v172
	v_and_b32_e32 v209, s14, v172
	v_pk_mul_f32 v[106:107], v[206:207], v[208:209]
	v_lshlrev_b32_e32 v210, 16, v165
	v_and_b32_e32 v211, s14, v165
	v_lshlrev_b32_e32 v212, 16, v173
	v_and_b32_e32 v213, s14, v173
	v_pk_mul_f32 v[108:109], v[210:211], v[212:213]
	v_lshlrev_b32_e32 v202, 16, v166
	v_and_b32_e32 v203, s14, v166
	v_lshlrev_b32_e32 v204, 16, v174
	v_and_b32_e32 v205, s14, v174
	v_pk_mul_f32 v[110:111], v[202:203], v[204:205]
	v_lshlrev_b32_e32 v206, 16, v167
	v_and_b32_e32 v207, s14, v167
	v_lshlrev_b32_e32 v208, 16, v175
	v_and_b32_e32 v209, s14, v175
	v_pk_mul_f32 v[112:113], v[206:207], v[208:209]
	global_load_dwordx4 v[160:163], v1, s[4:5] offset:2048
	global_load_dwordx4 v[164:167], v1, s[4:5] offset:2064
	global_load_dwordx4 v[168:171], v2, s[4:5]
	global_load_dwordx4 v[172:175], v2, s[4:5] offset:16
	s_add_u32 s4, s4, 0x1800
	s_addc_u32 s5, s5, 0
	s_add_i32 s12, s11, 3
	s_cmp_lt_u32 s12, 0x4000
	s_cselect_b32 s29, s3, s13
	s_and_b32 s27, s12, s29
	v_pk_mul_f32 v[234:235], v[20:21], v[68:69]
	v_pk_mul_f32 v[236:237], v[22:23], v[70:71]
	v_pk_mul_f32 v[238:239], v[24:25], v[72:73]
	v_pk_mul_f32 v[240:241], v[26:27], v[74:75]
	v_pk_mul_f32 v[242:243], v[28:29], v[76:77]
	v_pk_mul_f32 v[244:245], v[30:31], v[78:79]
	v_pk_mul_f32 v[246:247], v[32:33], v[80:81]
	v_pk_mul_f32 v[248:249], v[34:35], v[82:83]
	s_cmp_eq_u32 s27, 0
	s_cbranch_scc1 .Lcg9_np3
	v_pk_fma_f32 v[234:235], v[4:5], v[52:53], v[234:235]
	v_pk_fma_f32 v[236:237], v[6:7], v[54:55], v[236:237]
	v_pk_fma_f32 v[238:239], v[8:9], v[56:57], v[238:239]
	v_pk_fma_f32 v[240:241], v[10:11], v[58:59], v[240:241]
	v_pk_fma_f32 v[242:243], v[12:13], v[60:61], v[242:243]
	v_pk_fma_f32 v[244:245], v[14:15], v[62:63], v[244:245]
	v_pk_fma_f32 v[246:247], v[16:17], v[64:65], v[246:247]
	v_pk_fma_f32 v[248:249], v[18:19], v[66:67], v[248:249]

; __device__ __forceinline__ unsigned cvt_pk_bf16(float lo, float hi) { unsigned r; asm volatile("v_cvt_pk_bf16_f32 %0, %1, %2" : "=v"(r) : "v"(lo), "v"(hi)); return r; }
; __device__ __forceinline__ float bflo(unsigned w) { return __uint_as_float(w << 16); }
; __device__ __forceinline__ float bfhi(unsigned w) { return __uint_as_float(w & 0xffff0000u); }
; __device__ __forceinline__ void convgate_phase(const bf16_t* U, bf16_t* H, int rows, const float* ck, int gw, int NGW, int lane) {
;     ...
; #pragma unroll
;         for (int hf = 0; hf < 2; ++hf) {
;             const int c0 = lane * 16 + hf * 8;
;             u32x4 ow;
; #pragma unroll
;             for (int e = 0; e < 4; ++e) {
;                 const f32x2 w0 = *(const f32x2*)(ck + c0 + 2 * e), w1 = *(const f32x2*)(ck + D + c0 + 2 * e), w2 = *(const f32x2*)(ck + 2 * D + c0 + 2 * e);
;                 const float lo = bflo(bq[hf][e]) * (w0[0] * (bflo(cp[hf][e]) * bflo(vp[hf][e])) + w1[0] * (bflo(cq[hf][e]) * bflo(vq[hf][e])) + w2[0] * (bflo(cn[hf][e]) * bflo(vn[hf][e])));
;                 const float hi = bfhi(bq[hf][e]) * (w0[1] * (bfhi(cp[hf][e]) * bfhi(vp[hf][e])) + w1[1] * (bfhi(cq[hf][e]) * bfhi(vq[hf][e])) + w2[1] * (bfhi(cn[hf][e]) * bfhi(vn[hf][e])));
;                 ow[e] = cvt_pk_bf16(lo, hi);
;             }
;             *(u32x4*)(H + (size_t)row * D + c0) = ow;
;         }
.Lcg9_nn3:
	v_lshlrev_b32_e32 v202, 16, v146
	v_and_b32_e32 v203, s14, v146
	v_pk_mul_f32 v[234:235], v[234:235], v[202:203]
	v_lshlrev_b32_e32 v206, 16, v147
	v_and_b32_e32 v207, s14, v147
	v_pk_mul_f32 v[236:237], v[236:237], v[206:207]
	v_lshlrev_b32_e32 v210, 16, v148
	v_and_b32_e32 v211, s14, v148
	v_pk_mul_f32 v[238:239], v[238:239], v[210:211]
	v_lshlrev_b32_e32 v202, 16, v149
	v_and_b32_e32 v203, s14, v149
	v_pk_mul_f32 v[240:241], v[240:241], v[202:203]
	v_lshlrev_b32_e32 v206, 16, v150
	v_and_b32_e32 v207, s14, v150
	v_pk_mul_f32 v[242:243], v[242:243], v[206:207]
	v_lshlrev_b32_e32 v210, 16, v151
	v_and_b32_e32 v211, s14, v151
	v_pk_mul_f32 v[244:245], v[244:245], v[210:211]
	v_lshlrev_b32_e32 v202, 16, v152
	v_and_b32_e32 v203, s14, v152
	v_pk_mul_f32 v[246:247], v[246:247], v[202:203]
	v_lshlrev_b32_e32 v206, 16, v153
	v_and_b32_e32 v207, s14, v153
	v_pk_mul_f32 v[248:249], v[248:249], v[206:207]
	v_cvt_pk_bf16_f32 v84, v234, v235
	v_cvt_pk_bf16_f32 v85, v236, v237
	v_cvt_pk_bf16_f32 v86, v238, v239
	v_cvt_pk_bf16_f32 v87, v240, v241
	v_cvt_pk_bf16_f32 v88, v242, v243
	v_cvt_pk_bf16_f32 v89, v244, v245
	v_cvt_pk_bf16_f32 v90, v246, v247
	v_cvt_pk_bf16_f32 v91, v248, v249
	global_store_dwordx4 v1, v[84:87], s[8:9]
	global_store_dwordx4 v1, v[88:91], s[8:9] offset:16
	s_add_u32 s8, s8, 0x800
	s_addc_u32 s9, s9, 0
	global_load_dwordx4 v[146:149], v1, s[6:7]
	global_load_dwordx4 v[150:153], v1, s[6:7] offset:16
	s_add_u32 s6, s6, 0x1800
	s_addc_u32 s7, s7, 0
	s_waitcnt vmcnt(16)
	v_lshlrev_b32_e32 v202, 16, v114
	v_and_b32_e32 v203, s14, v114
	v_lshlrev_b32_e32 v204, 16, v122
	v_and_b32_e32 v205, s14, v122
	v_pk_mul_f32 v[52:53], v[202:203], v[204:205]
	v_lshlrev_b32_e32 v206, 16, v115
	v_and_b32_e32 v207, s14, v115
	v_lshlrev_b32_e32 v208, 16, v123
	v_and_b32_e32 v209, s14, v123
	v_pk_mul_f32 v[54:55], v[206:207], v[208:209]
	v_lshlrev_b32_e32 v210, 16, v116
	v_and_b32_e32 v211, s14, v116
	v_lshlrev_b32_e32 v212, 16, v124
	v_and_b32_e32 v213, s14, v124
	v_pk_mul_f32 v[56:57], v[210:211], v[212:213]
	v_lshlrev_b32_e32 v202, 16, v117
	v_and_b32_e32 v203, s14, v117
	v_lshlrev_b32_e32 v204, 16, v125
	v_and_b32_e32 v205, s14, v125
	v_pk_mul_f32 v[58:59], v[202:203], v[204:205]
	v_lshlrev_b32_e32 v206, 16, v118
	v_and_b32_e32 v207, s14, v118
	v_lshlrev_b32_e32 v208, 16, v126
	v_and_b32_e32 v209, s14, v126
	v_pk_mul_f32 v[60:61], v[206:207], v[208:209]
	v_lshlrev_b32_e32 v210, 16, v119
	v_and_b32_e32 v211, s14, v119
	v_lshlrev_b32_e32 v212, 16, v127
	v_and_b32_e32 v213, s14, v127
	v_pk_mul_f32 v[62:63], v[210:211], v[212:213]
	v_lshlrev_b32_e32 v202, 16, v120
	v_and_b32_e32 v203, s14, v120
	v_lshlrev_b32_e32 v204, 16, v128
	v_and_b32_e32 v205, s14, v128
	v_pk_mul_f32 v[64:65], v[202:203], v[204:205]
	v_lshlrev_b32_e32 v206, 16, v121
	v_and_b32_e32 v207, s14, v121
	v_lshlrev_b32_e32 v208, 16, v129
	v_and_b32_e32 v209, s14, v129
	v_pk_mul_f32 v[66:67], v[206:207], v[208:209]
	global_load_dwordx4 v[114:117], v1, s[4:5] offset:2048
	global_load_dwordx4 v[118:121], v1, s[4:5] offset:2064
	global_load_dwordx4 v[122:125], v2, s[4:5]
	global_load_dwordx4 v[126:129], v2, s[4:5] offset:16
	s_add_u32 s4, s4, 0x1800
	s_addc_u32 s5, s5, 0
	s_add_i32 s12, s11, 4
	s_cmp_lt_u32 s12, 0x4000
	s_cselect_b32 s29, s3, s13
	s_and_b32 s27, s12, s29
	v_pk_mul_f32 v[234:235], v[20:21], v[98:99]
	v_pk_mul_f32 v[236:237], v[22:23], v[100:101]
	v_pk_mul_f32 v[238:239], v[24:25], v[102:103]
	v_pk_mul_f32 v[240:241], v[26:27], v[104:105]
	v_pk_mul_f32 v[242:243], v[28:29], v[106:107]
	v_pk_mul_f32 v[244:245], v[30:31], v[108:109]
	v_pk_mul_f32 v[246:247], v[32:33], v[110:111]
	v_pk_mul_f32 v[248:249], v[34:35], v[112:113]
	s_cmp_eq_u32 s27, 0
	s_cbranch_scc1 .Lcg9_np4
	v_pk_fma_f32 v[234:235], v[4:5], v[68:69], v[234:235]
	v_pk_fma_f32 v[236:237], v[6:7], v[70:71], v[236:237]
	v_pk_fma_f32 v[238:239], v[8:9], v[72:73], v[238:239]
	v_pk_fma_f32 v[240:241], v[10:11], v[74:75], v[240:241]
	v_pk_fma_f32 v[242:243], v[12:13], v[76:77], v[242:243]
	v_pk_fma_f32 v[244:245], v[14:15], v[78:79], v[244:245]
	v_pk_fma_f32 v[246:247], v[16:17], v[80:81], v[246:247]
	v_pk_fma_f32 v[248:249], v[18:19], v[82:83], v[248:249]

; __device__ __forceinline__ unsigned cvt_pk_bf16(float lo, float hi) { unsigned r; asm volatile("v_cvt_pk_bf16_f32 %0, %1, %2" : "=v"(r) : "v"(lo), "v"(hi)); return r; }
; __device__ __forceinline__ float bflo(unsigned w) { return __uint_as_float(w << 16); }
; __device__ __forceinline__ float bfhi(unsigned w) { return __uint_as_float(w & 0xffff0000u); }
; __device__ __forceinline__ void convgate_phase(const bf16_t* U, bf16_t* H, int rows, const float* ck, int gw, int NGW, int lane) {
;     ...
; #pragma unroll
;         for (int hf = 0; hf < 2; ++hf) {
;             const int c0 = lane * 16 + hf * 8;
;             u32x4 ow;
; #pragma unroll
;             for (int e = 0; e < 4; ++e) {
;                 const f32x2 w0 = *(const f32x2*)(ck + c0 + 2 * e), w1 = *(const f32x2*)(ck + D + c0 + 2 * e), w2 = *(const f32x2*)(ck + 2 * D + c0 + 2 * e);
;                 const float lo = bflo(bq[hf][e]) * (w0[0] * (bflo(cp[hf][e]) * bflo(vp[hf][e])) + w1[0] * (bflo(cq[hf][e]) * bflo(vq[hf][e])) + w2[0] * (bflo(cn[hf][e]) * bflo(vn[hf][e])));
;                 const float hi = bfhi(bq[hf][e]) * (w0[1] * (bfhi(cp[hf][e]) * bfhi(vp[hf][e])) + w1[1] * (bfhi(cq[hf][e]) * bfhi(vq[hf][e])) + w2[1] * (bfhi(cn[hf][e]) * bfhi(vn[hf][e])));
;                 ow[e] = cvt_pk_bf16(lo, hi);
;             }
;             *(u32x4*)(H + (size_t)row * D + c0) = ow;
;         }
.Lcg9_nn4:
	v_lshlrev_b32_e32 v202, 16, v176
	v_and_b32_e32 v203, s14, v176
	v_pk_mul_f32 v[234:235], v[234:235], v[202:203]
	v_lshlrev_b32_e32 v206, 16, v177
	v_and_b32_e32 v207, s14, v177
	v_pk_mul_f32 v[236:237], v[236:237], v[206:207]
	v_lshlrev_b32_e32 v210, 16, v178
	v_and_b32_e32 v211, s14, v178
	v_pk_mul_f32 v[238:239], v[238:239], v[210:211]
	v_lshlrev_b32_e32 v202, 16, v179
	v_and_b32_e32 v203, s14, v179
	v_pk_mul_f32 v[240:241], v[240:241], v[202:203]
	v_lshlrev_b32_e32 v206, 16, v180
	v_and_b32_e32 v207, s14, v180
	v_pk_mul_f32 v[242:243], v[242:243], v[206:207]
	v_lshlrev_b32_e32 v210, 16, v181
	v_and_b32_e32 v211, s14, v181
	v_pk_mul_f32 v[244:245], v[244:245], v[210:211]
	v_lshlrev_b32_e32 v202, 16, v182
	v_and_b32_e32 v203, s14, v182
	v_pk_mul_f32 v[246:247], v[246:247], v[202:203]
	v_lshlrev_b32_e32 v206, 16, v183
	v_and_b32_e32 v207, s14, v183
	v_pk_mul_f32 v[248:249], v[248:249], v[206:207]
	v_cvt_pk_bf16_f32 v84, v234, v235
	v_cvt_pk_bf16_f32 v85, v236, v237
	v_cvt_pk_bf16_f32 v86, v238, v239
	v_cvt_pk_bf16_f32 v87, v240, v241
	v_cvt_pk_bf16_f32 v88, v242, v243
	v_cvt_pk_bf16_f32 v89, v244, v245
	v_cvt_pk_bf16_f32 v90, v246, v247
	v_cvt_pk_bf16_f32 v91, v248, v249
	global_store_dwordx4 v1, v[84:87], s[8:9]
	global_store_dwordx4 v1, v[88:91], s[8:9] offset:16
	s_add_u32 s8, s8, 0x800
	s_addc_u32 s9, s9, 0
	global_load_dwordx4 v[176:179], v1, s[6:7]
	global_load_dwordx4 v[180:183], v1, s[6:7] offset:16
	s_add_u32 s6, s6, 0x1800
	s_addc_u32 s7, s7, 0
	s_waitcnt vmcnt(16)
	v_lshlrev_b32_e32 v202, 16, v130
	v_and_b32_e32 v203, s14, v130
	v_lshlrev_b32_e32 v204, 16, v138
	v_and_b32_e32 v205, s14, v138
	v_pk_mul_f32 v[68:69], v[202:203], v[204:205]
	v_lshlrev_b32_e32 v206, 16, v131
	v_and_b32_e32 v207, s14, v131
	v_lshlrev_b32_e32 v208, 16, v139
	v_and_b32_e32 v209, s14, v139
	v_pk_mul_f32 v[70:71], v[206:207], v[208:209]
	v_lshlrev_b32_e32 v210, 16, v132
	v_and_b32_e32 v211, s14, v132
	v_lshlrev_b32_e32 v212, 16, v140
	v_and_b32_e32 v213, s14, v140
	v_pk_mul_f32 v[72:73], v[210:211], v[212:213]
	v_lshlrev_b32_e32 v202, 16, v133
	v_and_b32_e32 v203, s14, v133
	v_lshlrev_b32_e32 v204, 16, v141
	v_and_b32_e32 v205, s14, v141
	v_pk_mul_f32 v[74:75], v[202:203], v[204:205]
	v_lshlrev_b32_e32 v206, 16, v134
	v_and_b32_e32 v207, s14, v134
	v_lshlrev_b32_e32 v208, 16, v142
	v_and_b32_e32 v209, s14, v142
	v_pk_mul_f32 v[76:77], v[206:207], v[208:209]
	v_lshlrev_b32_e32 v210, 16, v135
	v_and_b32_e32 v211, s14, v135
	v_lshlrev_b32_e32 v212, 16, v143
	v_and_b32_e32 v213, s14, v143
	v_pk_mul_f32 v[78:79], v[210:211], v[212:213]
	v_lshlrev_b32_e32 v202, 16, v136
	v_and_b32_e32 v203, s14, v136
	v_lshlrev_b32_e32 v204, 16, v144
	v_and_b32_e32 v205, s14, v144
	v_pk_mul_f32 v[80:81], v[202:203], v[204:205]
	v_lshlrev_b32_e32 v206, 16, v137
	v_and_b32_e32 v207, s14, v137
	v_lshlrev_b32_e32 v208, 16, v145
	v_and_b32_e32 v209, s14, v145
	v_pk_mul_f32 v[82:83], v[206:207], v[208:209]
	global_load_dwordx4 v[130:133], v1, s[4:5] offset:2048
	global_load_dwordx4 v[134:137], v1, s[4:5] offset:2064
	global_load_dwordx4 v[138:141], v2, s[4:5]
	global_load_dwordx4 v[142:145], v2, s[4:5] offset:16
	s_add_u32 s4, s4, 0x1800
	s_addc_u32 s5, s5, 0
	s_add_i32 s12, s11, 5
	s_cmp_lt_u32 s12, 0x4000
	s_cselect_b32 s29, s3, s13
	s_and_b32 s27, s12, s29
	v_pk_mul_f32 v[234:235], v[20:21], v[52:53]
	v_pk_mul_f32 v[236:237], v[22:23], v[54:55]
	v_pk_mul_f32 v[238:239], v[24:25], v[56:57]
	v_pk_mul_f32 v[240:241], v[26:27], v[58:59]
	v_pk_mul_f32 v[242:243], v[28:29], v[60:61]
	v_pk_mul_f32 v[244:245], v[30:31], v[62:63]
	v_pk_mul_f32 v[246:247], v[32:33], v[64:65]
	v_pk_mul_f32 v[248:249], v[34:35], v[66:67]
	s_cmp_eq_u32 s27, 0
	s_cbranch_scc1 .Lcg9_np5
	v_pk_fma_f32 v[234:235], v[4:5], v[98:99], v[234:235]
	v_pk_fma_f32 v[236:237], v[6:7], v[100:101], v[236:237]
	v_pk_fma_f32 v[238:239], v[8:9], v[102:103], v[238:239]
	v_pk_fma_f32 v[240:241], v[10:11], v[104:105], v[240:241]
	v_pk_fma_f32 v[242:243], v[12:13], v[106:107], v[242:243]
	v_pk_fma_f32 v[244:245], v[14:15], v[108:109], v[244:245]
	v_pk_fma_f32 v[246:247], v[16:17], v[110:111], v[246:247]
	v_pk_fma_f32 v[248:249], v[18:19], v[112:113], v[248:249]

; __device__ __forceinline__ unsigned cvt_pk_bf16(float lo, float hi) { unsigned r; asm volatile("v_cvt_pk_bf16_f32 %0, %1, %2" : "=v"(r) : "v"(lo), "v"(hi)); return r; }
; __device__ __forceinline__ float bflo(unsigned w) { return __uint_as_float(w << 16); }
; __device__ __forceinline__ float bfhi(unsigned w) { return __uint_as_float(w & 0xffff0000u); }
; __device__ __forceinline__ void convgate_phase(const bf16_t* U, bf16_t* H, int rows, const float* ck, int gw, int NGW, int lane) {
;     ...
; #pragma unroll
;         for (int hf = 0; hf < 2; ++hf) {
;             const int c0 = lane * 16 + hf * 8;
;             u32x4 ow;
; #pragma unroll
;             for (int e = 0; e < 4; ++e) {
;                 const f32x2 w0 = *(const f32x2*)(ck + c0 + 2 * e), w1 = *(const f32x2*)(ck + D + c0 + 2 * e), w2 = *(const f32x2*)(ck + 2 * D + c0 + 2 * e);
;                 const float lo = bflo(bq[hf][e]) * (w0[0] * (bflo(cp[hf][e]) * bflo(vp[hf][e])) + w1[0] * (bflo(cq[hf][e]) * bflo(vq[hf][e])) + w2[0] * (bflo(cn[hf][e]) * bflo(vn[hf][e])));
;                 const float hi = bfhi(bq[hf][e]) * (w0[1] * (bfhi(cp[hf][e]) * bfhi(vp[hf][e])) + w1[1] * (bfhi(cq[hf][e]) * bfhi(vq[hf][e])) + w2[1] * (bfhi(cn[hf][e]) * bfhi(vn[hf][e])));
;                 ow[e] = cvt_pk_bf16(lo, hi);
;             }
;             *(u32x4*)(H + (size_t)row * D + c0) = ow;
;         }
.Lcg9_nn5:
	v_lshlrev_b32_e32 v202, 16, v226
	v_and_b32_e32 v203, s14, v226
	v_pk_mul_f32 v[234:235], v[234:235], v[202:203]
	v_lshlrev_b32_e32 v206, 16, v227
	v_and_b32_e32 v207, s14, v227
	v_pk_mul_f32 v[236:237], v[236:237], v[206:207]
	v_lshlrev_b32_e32 v210, 16, v228
	v_and_b32_e32 v211, s14, v228
	v_pk_mul_f32 v[238:239], v[238:239], v[210:211]
	v_lshlrev_b32_e32 v202, 16, v229
	v_and_b32_e32 v203, s14, v229
	v_pk_mul_f32 v[240:241], v[240:241], v[202:203]
	v_lshlrev_b32_e32 v206, 16, v230
	v_and_b32_e32 v207, s14, v230
	v_pk_mul_f32 v[242:243], v[242:243], v[206:207]
	v_lshlrev_b32_e32 v210, 16, v231
	v_and_b32_e32 v211, s14, v231
	v_pk_mul_f32 v[244:245], v[244:245], v[210:211]
	v_lshlrev_b32_e32 v202, 16, v232
	v_and_b32_e32 v203, s14, v232
	v_pk_mul_f32 v[246:247], v[246:247], v[202:203]
	v_lshlrev_b32_e32 v206, 16, v233
	v_and_b32_e32 v207, s14, v233
	v_pk_mul_f32 v[248:249], v[248:249], v[206:207]
	v_cvt_pk_bf16_f32 v84, v234, v235
	v_cvt_pk_bf16_f32 v85, v236, v237
	v_cvt_pk_bf16_f32 v86, v238, v239
	v_cvt_pk_bf16_f32 v87, v240, v241
	v_cvt_pk_bf16_f32 v88, v242, v243
	v_cvt_pk_bf16_f32 v89, v244, v245
	v_cvt_pk_bf16_f32 v90, v246, v247
	v_cvt_pk_bf16_f32 v91, v248, v249
	global_store_dwordx4 v1, v[84:87], s[8:9]
	global_store_dwordx4 v1, v[88:91], s[8:9] offset:16
	s_add_u32 s8, s8, 0x800
	s_addc_u32 s9, s9, 0
	global_load_dwordx4 v[226:229], v1, s[6:7]
	global_load_dwordx4 v[230:233], v1, s[6:7] offset:16
	s_add_u32 s6, s6, 0x1800
	s_addc_u32 s7, s7, 0
	s_waitcnt vmcnt(16)
	v_lshlrev_b32_e32 v202, 16, v160
	v_and_b32_e32 v203, s14, v160
	v_lshlrev_b32_e32 v204, 16, v168
	v_and_b32_e32 v205, s14, v168
	v_pk_mul_f32 v[98:99], v[202:203], v[204:205]
	v_lshlrev_b32_e32 v206, 16, v161
	v_and_b32_e32 v207, s14, v161
	v_lshlrev_b32_e32 v208, 16, v169
	v_and_b32_e32 v209, s14, v169
	v_pk_mul_f32 v[100:101], v[206:207], v[208:209]
	v_lshlrev_b32_e32 v210, 16, v162
	v_and_b32_e32 v211, s14, v162
	v_lshlrev_b32_e32 v212, 16, v170
	v_and_b32_e32 v213, s14, v170
	v_pk_mul_f32 v[102:103], v[210:211], v[212:213]
	v_lshlrev_b32_e32 v202, 16, v163
	v_and_b32_e32 v203, s14, v163
	v_lshlrev_b32_e32 v204, 16, v171
	v_and_b32_e32 v205, s14, v171
	v_pk_mul_f32 v[104:105], v[202:203], v[204:205]
	v_lshlrev_b32_e32 v206, 16, v164
	v_and_b32_e32 v207, s14, v164
	v_lshlrev_b32_e32 v208, 16, v172
	v_and_b32_e32 v209, s14, v172
	v_pk_mul_f32 v[106:107], v[206:207], v[208:209]
	v_lshlrev_b32_e32 v210, 16, v165
	v_and_b32_e32 v211, s14, v165
	v_lshlrev_b32_e32 v212, 16, v173
	v_and_b32_e32 v213, s14, v173
	v_pk_mul_f32 v[108:109], v[210:211], v[212:213]
	v_lshlrev_b32_e32 v202, 16, v166
	v_and_b32_e32 v203, s14, v166
	v_lshlrev_b32_e32 v204, 16, v174
	v_and_b32_e32 v205, s14, v174
	v_pk_mul_f32 v[110:111], v[202:203], v[204:205]
	v_lshlrev_b32_e32 v206, 16, v167
	v_and_b32_e32 v207, s14, v167
	v_lshlrev_b32_e32 v208, 16, v175
	v_and_b32_e32 v209, s14, v175
	v_pk_mul_f32 v[112:113], v[206:207], v[208:209]
	s_add_i32 s12, s11, 6
	s_cmp_lt_u32 s12, 0x4000
	s_cselect_b32 s29, s3, s13
	s_and_b32 s27, s12, s29
	v_pk_mul_f32 v[234:235], v[20:21], v[68:69]
	v_pk_mul_f32 v[236:237], v[22:23], v[70:71]
	v_pk_mul_f32 v[238:239], v[24:25], v[72:73]
	v_pk_mul_f32 v[240:241], v[26:27], v[74:75]
	v_pk_mul_f32 v[242:243], v[28:29], v[76:77]
	v_pk_mul_f32 v[244:245], v[30:31], v[78:79]
	v_pk_mul_f32 v[246:247], v[32:33], v[80:81]
	v_pk_mul_f32 v[248:249], v[34:35], v[82:83]
	s_cmp_eq_u32 s27, 0
	s_cbranch_scc1 .Lcg9_np6
	v_pk_fma_f32 v[234:235], v[4:5], v[52:53], v[234:235]
	v_pk_fma_f32 v[236:237], v[6:7], v[54:55], v[236:237]
	v_pk_fma_f32 v[238:239], v[8:9], v[56:57], v[238:239]
	v_pk_fma_f32 v[240:241], v[10:11], v[58:59], v[240:241]
	v_pk_fma_f32 v[242:243], v[12:13], v[60:61], v[242:243]
	v_pk_fma_f32 v[244:245], v[14:15], v[62:63], v[244:245]
	v_pk_fma_f32 v[246:247], v[16:17], v[64:65], v[246:247]
	v_pk_fma_f32 v[248:249], v[18:19], v[66:67], v[248:249]

; __device__ __forceinline__ unsigned cvt_pk_bf16(float lo, float hi) { unsigned r; asm volatile("v_cvt_pk_bf16_f32 %0, %1, %2" : "=v"(r) : "v"(lo), "v"(hi)); return r; }
; __device__ __forceinline__ float bflo(unsigned w) { return __uint_as_float(w << 16); }
; __device__ __forceinline__ float bfhi(unsigned w) { return __uint_as_float(w & 0xffff0000u); }
; __device__ __forceinline__ void convgate_phase(const bf16_t* U, bf16_t* H, int rows, const float* ck, int gw, int NGW, int lane) {
;     ...
; #pragma unroll
;         for (int hf = 0; hf < 2; ++hf) {
;             const int c0 = lane * 16 + hf * 8;
;             u32x4 ow;
; #pragma unroll
;             for (int e = 0; e < 4; ++e) {
;                 const f32x2 w0 = *(const f32x2*)(ck + c0 + 2 * e), w1 = *(const f32x2*)(ck + D + c0 + 2 * e), w2 = *(const f32x2*)(ck + 2 * D + c0 + 2 * e);
;                 const float lo = bflo(bq[hf][e]) * (w0[0] * (bflo(cp[hf][e]) * bflo(vp[hf][e])) + w1[0] * (bflo(cq[hf][e]) * bflo(vq[hf][e])) + w2[0] * (bflo(cn[hf][e]) * bflo(vn[hf][e])));
;                 const float hi = bfhi(bq[hf][e]) * (w0[1] * (bfhi(cp[hf][e]) * bfhi(vp[hf][e])) + w1[1] * (bfhi(cq[hf][e]) * bfhi(vq[hf][e])) + w2[1] * (bfhi(cn[hf][e]) * bfhi(vn[hf][e])));
;                 ow[e] = cvt_pk_bf16(lo, hi);
;             }
;             *(u32x4*)(H + (size_t)row * D + c0) = ow;
;         }
.Lcg9_nn6:
	v_lshlrev_b32_e32 v202, 16, v146
	v_and_b32_e32 v203, s14, v146
	v_pk_mul_f32 v[234:235], v[234:235], v[202:203]
	v_lshlrev_b32_e32 v206, 16, v147
	v_and_b32_e32 v207, s14, v147
	v_pk_mul_f32 v[236:237], v[236:237], v[206:207]
	v_lshlrev_b32_e32 v210, 16, v148
	v_and_b32_e32 v211, s14, v148
	v_pk_mul_f32 v[238:239], v[238:239], v[210:211]
	v_lshlrev_b32_e32 v202, 16, v149
	v_and_b32_e32 v203, s14, v149
	v_pk_mul_f32 v[240:241], v[240:241], v[202:203]
	v_lshlrev_b32_e32 v206, 16, v150
	v_and_b32_e32 v207, s14, v150
	v_pk_mul_f32 v[242:243], v[242:243], v[206:207]
	v_lshlrev_b32_e32 v210, 16, v151
	v_and_b32_e32 v211, s14, v151
	v_pk_mul_f32 v[244:245], v[244:245], v[210:211]
	v_lshlrev_b32_e32 v202, 16, v152
	v_and_b32_e32 v203, s14, v152
	v_pk_mul_f32 v[246:247], v[246:247], v[202:203]
	v_lshlrev_b32_e32 v206, 16, v153
	v_and_b32_e32 v207, s14, v153
	v_pk_mul_f32 v[248:249], v[248:249], v[206:207]
	v_cvt_pk_bf16_f32 v84, v234, v235
	v_cvt_pk_bf16_f32 v85, v236, v237
	v_cvt_pk_bf16_f32 v86, v238, v239
	v_cvt_pk_bf16_f32 v87, v240, v241
	v_cvt_pk_bf16_f32 v88, v242, v243
	v_cvt_pk_bf16_f32 v89, v244, v245
	v_cvt_pk_bf16_f32 v90, v246, v247
	v_cvt_pk_bf16_f32 v91, v248, v249
	global_store_dwordx4 v1, v[84:87], s[8:9]
	global_store_dwordx4 v1, v[88:91], s[8:9] offset:16
	s_add_u32 s8, s8, 0x800
	s_addc_u32 s9, s9, 0
	s_waitcnt vmcnt(10)
	v_lshlrev_b32_e32 v202, 16, v114
	v_and_b32_e32 v203, s14, v114
	v_lshlrev_b32_e32 v204, 16, v122
	v_and_b32_e32 v205, s14, v122
	v_pk_mul_f32 v[52:53], v[202:203], v[204:205]
	v_lshlrev_b32_e32 v206, 16, v115
	v_and_b32_e32 v207, s14, v115
	v_lshlrev_b32_e32 v208, 16, v123
	v_and_b32_e32 v209, s14, v123
	v_pk_mul_f32 v[54:55], v[206:207], v[208:209]
	v_lshlrev_b32_e32 v210, 16, v116
	v_and_b32_e32 v211, s14, v116
	v_lshlrev_b32_e32 v212, 16, v124
	v_and_b32_e32 v213, s14, v124
	v_pk_mul_f32 v[56:57], v[210:211], v[212:213]
	v_lshlrev_b32_e32 v202, 16, v117
	v_and_b32_e32 v203, s14, v117
	v_lshlrev_b32_e32 v204, 16, v125
	v_and_b32_e32 v205, s14, v125
	v_pk_mul_f32 v[58:59], v[202:203], v[204:205]
	v_lshlrev_b32_e32 v206, 16, v118
	v_and_b32_e32 v207, s14, v118
	v_lshlrev_b32_e32 v208, 16, v126
	v_and_b32_e32 v209, s14, v126
	v_pk_mul_f32 v[60:61], v[206:207], v[208:209]
	v_lshlrev_b32_e32 v210, 16, v119
	v_and_b32_e32 v211, s14, v119
	v_lshlrev_b32_e32 v212, 16, v127
	v_and_b32_e32 v213, s14, v127
	v_pk_mul_f32 v[62:63], v[210:211], v[212:213]
	v_lshlrev_b32_e32 v202, 16, v120
	v_and_b32_e32 v203, s14, v120
	v_lshlrev_b32_e32 v204, 16, v128
	v_and_b32_e32 v205, s14, v128
	v_pk_mul_f32 v[64:65], v[202:203], v[204:205]
	v_lshlrev_b32_e32 v206, 16, v121
	v_and_b32_e32 v207, s14, v121
	v_lshlrev_b32_e32 v208, 16, v129
	v_and_b32_e32 v209, s14, v129
	v_pk_mul_f32 v[66:67], v[206:207], v[208:209]
	s_add_i32 s12, s11, 7
	s_cmp_lt_u32 s12, 0x4000
	s_cselect_b32 s29, s3, s13
	s_and_b32 s27, s12, s29
	v_pk_mul_f32 v[234:235], v[20:21], v[98:99]
	v_pk_mul_f32 v[236:237], v[22:23], v[100:101]
	v_pk_mul_f32 v[238:239], v[24:25], v[102:103]
	v_pk_mul_f32 v[240:241], v[26:27], v[104:105]
	v_pk_mul_f32 v[242:243], v[28:29], v[106:107]
	v_pk_mul_f32 v[244:245], v[30:31], v[108:109]
	v_pk_mul_f32 v[246:247], v[32:33], v[110:111]
	v_pk_mul_f32 v[248:249], v[34:35], v[112:113]
	s_cmp_eq_u32 s27, 0
	s_cbranch_scc1 .Lcg9_np7
	v_pk_fma_f32 v[234:235], v[4:5], v[68:69], v[234:235]
	v_pk_fma_f32 v[236:237], v[6:7], v[70:71], v[236:237]
	v_pk_fma_f32 v[238:239], v[8:9], v[72:73], v[238:239]
	v_pk_fma_f32 v[240:241], v[10:11], v[74:75], v[240:241]
	v_pk_fma_f32 v[242:243], v[12:13], v[76:77], v[242:243]
	v_pk_fma_f32 v[244:245], v[14:15], v[78:79], v[244:245]
	v_pk_fma_f32 v[246:247], v[16:17], v[80:81], v[246:247]
	v_pk_fma_f32 v[248:249], v[18:19], v[82:83], v[248:249]

; __device__ __forceinline__ unsigned cvt_pk_bf16(float lo, float hi) { unsigned r; asm volatile("v_cvt_pk_bf16_f32 %0, %1, %2" : "=v"(r) : "v"(lo), "v"(hi)); return r; }
; __device__ __forceinline__ float bflo(unsigned w) { return __uint_as_float(w << 16); }
; __device__ __forceinline__ float bfhi(unsigned w) { return __uint_as_float(w & 0xffff0000u); }
; __device__ __forceinline__ void convgate_phase(const bf16_t* U, bf16_t* H, int rows, const float* ck, int gw, int NGW, int lane) {
;     ...
; #pragma unroll
;         for (int hf = 0; hf < 2; ++hf) {
;             const int c0 = lane * 16 + hf * 8;
;             u32x4 ow;
; #pragma unroll
;             for (int e = 0; e < 4; ++e) {
;                 const f32x2 w0 = *(const f32x2*)(ck + c0 + 2 * e), w1 = *(const f32x2*)(ck + D + c0 + 2 * e), w2 = *(const f32x2*)(ck + 2 * D + c0 + 2 * e);
;                 const float lo = bflo(bq[hf][e]) * (w0[0] * (bflo(cp[hf][e]) * bflo(vp[hf][e])) + w1[0] * (bflo(cq[hf][e]) * bflo(vq[hf][e])) + w2[0] * (bflo(cn[hf][e]) * bflo(vn[hf][e])));
;                 const float hi = bfhi(bq[hf][e]) * (w0[1] * (bfhi(cp[hf][e]) * bfhi(vp[hf][e])) + w1[1] * (bfhi(cq[hf][e]) * bfhi(vq[hf][e])) + w2[1] * (bfhi(cn[hf][e]) * bfhi(vn[hf][e])));
;                 ow[e] = cvt_pk_bf16(lo, hi);
;             }
;             *(u32x4*)(H + (size_t)row * D + c0) = ow;
;         }
.Lcg9_nn7:
	v_lshlrev_b32_e32 v202, 16, v176
	v_and_b32_e32 v203, s14, v176
	v_pk_mul_f32 v[234:235], v[234:235], v[202:203]
	v_lshlrev_b32_e32 v206, 16, v177
	v_and_b32_e32 v207, s14, v177
	v_pk_mul_f32 v[236:237], v[236:237], v[206:207]
	v_lshlrev_b32_e32 v210, 16, v178
	v_and_b32_e32 v211, s14, v178
	v_pk_mul_f32 v[238:239], v[238:239], v[210:211]
	v_lshlrev_b32_e32 v202, 16, v179
	v_and_b32_e32 v203, s14, v179
	v_pk_mul_f32 v[240:241], v[240:241], v[202:203]
	v_lshlrev_b32_e32 v206, 16, v180
	v_and_b32_e32 v207, s14, v180
	v_pk_mul_f32 v[242:243], v[242:243], v[206:207]
	v_lshlrev_b32_e32 v210, 16, v181
	v_and_b32_e32 v211, s14, v181
	v_pk_mul_f32 v[244:245], v[244:245], v[210:211]
	v_lshlrev_b32_e32 v202, 16, v182
	v_and_b32_e32 v203, s14, v182
	v_pk_mul_f32 v[246:247], v[246:247], v[202:203]
	v_lshlrev_b32_e32 v206, 16, v183
	v_and_b32_e32 v207, s14, v183
	v_pk_mul_f32 v[248:249], v[248:249], v[206:207]
	v_cvt_pk_bf16_f32 v84, v234, v235
	v_cvt_pk_bf16_f32 v85, v236, v237
	v_cvt_pk_bf16_f32 v86, v238, v239
	v_cvt_pk_bf16_f32 v87, v240, v241
	v_cvt_pk_bf16_f32 v88, v242, v243
	v_cvt_pk_bf16_f32 v89, v244, v245
	v_cvt_pk_bf16_f32 v90, v246, v247
	v_cvt_pk_bf16_f32 v91, v248, v249
	global_store_dwordx4 v1, v[84:87], s[8:9]
	global_store_dwordx4 v1, v[88:91], s[8:9] offset:16
	s_add_u32 s8, s8, 0x800
	s_addc_u32 s9, s9, 0
	s_waitcnt vmcnt(4)
	v_lshlrev_b32_e32 v202, 16, v130
	v_and_b32_e32 v203, s14, v130
	v_lshlrev_b32_e32 v204, 16, v138
	v_and_b32_e32 v205, s14, v138
	v_pk_mul_f32 v[68:69], v[202:203], v[204:205]
	v_lshlrev_b32_e32 v206, 16, v131
	v_and_b32_e32 v207, s14, v131
	v_lshlrev_b32_e32 v208, 16, v139
	v_and_b32_e32 v209, s14, v139
	v_pk_mul_f32 v[70:71], v[206:207], v[208:209]
	v_lshlrev_b32_e32 v210, 16, v132
	v_and_b32_e32 v211, s14, v132
	v_lshlrev_b32_e32 v212, 16, v140
	v_and_b32_e32 v213, s14, v140
	v_pk_mul_f32 v[72:73], v[210:211], v[212:213]
	v_lshlrev_b32_e32 v202, 16, v133
	v_and_b32_e32 v203, s14, v133
	v_lshlrev_b32_e32 v204, 16, v141
	v_and_b32_e32 v205, s14, v141
	v_pk_mul_f32 v[74:75], v[202:203], v[204:205]
	v_lshlrev_b32_e32 v206, 16, v134
	v_and_b32_e32 v207, s14, v134
	v_lshlrev_b32_e32 v208, 16, v142
	v_and_b32_e32 v209, s14, v142
	v_pk_mul_f32 v[76:77], v[206:207], v[208:209]
	v_lshlrev_b32_e32 v210, 16, v135
	v_and_b32_e32 v211, s14, v135
	v_lshlrev_b32_e32 v212, 16, v143
	v_and_b32_e32 v213, s14, v143
	v_pk_mul_f32 v[78:79], v[210:211], v[212:213]
	v_lshlrev_b32_e32 v202, 16, v136
	v_and_b32_e32 v203, s14, v136
	v_lshlrev_b32_e32 v204, 16, v144
	v_and_b32_e32 v205, s14, v144
	v_pk_mul_f32 v[80:81], v[202:203], v[204:205]
	v_lshlrev_b32_e32 v206, 16, v137
	v_and_b32_e32 v207, s14, v137
	v_lshlrev_b32_e32 v208, 16, v145
	v_and_b32_e32 v209, s14, v145
	v_pk_mul_f32 v[82:83], v[206:207], v[208:209]
	s_add_i32 s12, s11, 8
	s_cmp_lt_u32 s12, 0x4000
	s_cselect_b32 s29, s3, s13
	s_and_b32 s27, s12, s29
	v_pk_mul_f32 v[234:235], v[20:21], v[52:53]
	v_pk_mul_f32 v[236:237], v[22:23], v[54:55]
	v_pk_mul_f32 v[238:239], v[24:25], v[56:57]
	v_pk_mul_f32 v[240:241], v[26:27], v[58:59]
	v_pk_mul_f32 v[242:243], v[28:29], v[60:61]
	v_pk_mul_f32 v[244:245], v[30:31], v[62:63]
	v_pk_mul_f32 v[246:247], v[32:33], v[64:65]
	v_pk_mul_f32 v[248:249], v[34:35], v[66:67]
	s_cmp_eq_u32 s27, 0
	s_cbranch_scc1 .Lcg9_np8
	v_pk_fma_f32 v[234:235], v[4:5], v[98:99], v[234:235]
	v_pk_fma_f32 v[236:237], v[6:7], v[100:101], v[236:237]
	v_pk_fma_f32 v[238:239], v[8:9], v[102:103], v[238:239]
	v_pk_fma_f32 v[240:241], v[10:11], v[104:105], v[240:241]
	v_pk_fma_f32 v[242:243], v[12:13], v[106:107], v[242:243]
	v_pk_fma_f32 v[244:245], v[14:15], v[108:109], v[244:245]
	v_pk_fma_f32 v[246:247], v[16:17], v[110:111], v[246:247]
	v_pk_fma_f32 v[248:249], v[18:19], v[112:113], v[248:249]

; __device__ __forceinline__ unsigned cvt_pk_bf16(float lo, float hi) { unsigned r; asm volatile("v_cvt_pk_bf16_f32 %0, %1, %2" : "=v"(r) : "v"(lo), "v"(hi)); return r; }
; __device__ __forceinline__ float bflo(unsigned w) { return __uint_as_float(w << 16); }
; __device__ __forceinline__ float bfhi(unsigned w) { return __uint_as_float(w & 0xffff0000u); }
; __device__ __forceinline__ void convgate_phase(const bf16_t* U, bf16_t* H, int rows, const float* ck, int gw, int NGW, int lane) {
;     ...
; #pragma unroll
;         for (int hf = 0; hf < 2; ++hf) {
;             const int c0 = lane * 16 + hf * 8;
;             u32x4 ow;
; #pragma unroll
;             for (int e = 0; e < 4; ++e) {
;                 const f32x2 w0 = *(const f32x2*)(ck + c0 + 2 * e), w1 = *(const f32x2*)(ck + D + c0 + 2 * e), w2 = *(const f32x2*)(ck + 2 * D + c0 + 2 * e);
;                 const float lo = bflo(bq[hf][e]) * (w0[0] * (bflo(cp[hf][e]) * bflo(vp[hf][e])) + w1[0] * (bflo(cq[hf][e]) * bflo(vq[hf][e])) + w2[0] * (bflo(cn[hf][e]) * bflo(vn[hf][e])));
;                 const float hi = bfhi(bq[hf][e]) * (w0[1] * (bfhi(cp[hf][e]) * bfhi(vp[hf][e])) + w1[1] * (bfhi(cq[hf][e]) * bfhi(vq[hf][e])) + w2[1] * (bfhi(cn[hf][e]) * bfhi(vn[hf][e])));
;                 ow[e] = cvt_pk_bf16(lo, hi);
;             }
;             *(u32x4*)(H + (size_t)row * D + c0) = ow;
;         }
.Lcg9_nn8:
	v_lshlrev_b32_e32 v202, 16, v226
	v_and_b32_e32 v203, s14, v226
	v_pk_mul_f32 v[234:235], v[234:235], v[202:203]
	v_lshlrev_b32_e32 v206, 16, v227
	v_and_b32_e32 v207, s14, v227
	v_pk_mul_f32 v[236:237], v[236:237], v[206:207]
	v_lshlrev_b32_e32 v210, 16, v228
	v_and_b32_e32 v211, s14, v228
	v_pk_mul_f32 v[238:239], v[238:239], v[210:211]
	v_lshlrev_b32_e32 v202, 16, v229
	v_and_b32_e32 v203, s14, v229
	v_pk_mul_f32 v[240:241], v[240:241], v[202:203]
	v_lshlrev_b32_e32 v206, 16, v230
	v_and_b32_e32 v207, s14, v230
	v_pk_mul_f32 v[242:243], v[242:243], v[206:207]
	v_lshlrev_b32_e32 v210, 16, v231
	v_and_b32_e32 v211, s14, v231
	v_pk_mul_f32 v[244:245], v[244:245], v[210:211]
	v_lshlrev_b32_e32 v202, 16, v232
	v_and_b32_e32 v203, s14, v232
	v_pk_mul_f32 v[246:247], v[246:247], v[202:203]
	v_lshlrev_b32_e32 v206, 16, v233
	v_and_b32_e32 v207, s14, v233
	v_pk_mul_f32 v[248:249], v[248:249], v[206:207]
	v_cvt_pk_bf16_f32 v84, v234, v235
	v_cvt_pk_bf16_f32 v85, v236, v237
	v_cvt_pk_bf16_f32 v86, v238, v239
	v_cvt_pk_bf16_f32 v87, v240, v241
	v_cvt_pk_bf16_f32 v88, v242, v243
	v_cvt_pk_bf16_f32 v89, v244, v245
	v_cvt_pk_bf16_f32 v90, v246, v247
	v_cvt_pk_bf16_f32 v91, v248, v249
	global_store_dwordx4 v1, v[84:87], s[8:9]
	global_store_dwordx4 v1, v[88:91], s[8:9] offset:16
	s_add_u32 s8, s8, 0x800
	s_addc_u32 s9, s9, 0
	s_branch .Lcg_done

; __device__ __forceinline__ unsigned cvt_pk_bf16(float lo, float hi) { unsigned r; asm volatile("v_cvt_pk_bf16_f32 %0, %1, %2" : "=v"(r) : "v"(lo), "v"(hi)); return r; }
; __device__ __forceinline__ float bflo(unsigned w) { return __uint_as_float(w << 16); }
; __device__ __forceinline__ float bfhi(unsigned w) { return __uint_as_float(w & 0xffff0000u); }
; __device__ __forceinline__ void convgate_phase(const bf16_t* U, bf16_t* H, int rows, const float* ck, int gw, int NGW, int lane) {
;     ...
; #pragma unroll
;         for (int hf = 0; hf < 2; ++hf) {
;             const int c0 = lane * 16 + hf * 8;
;             u32x4 ow;
; #pragma unroll
;             for (int e = 0; e < 4; ++e) {
;                 const f32x2 w0 = *(const f32x2*)(ck + c0 + 2 * e), w1 = *(const f32x2*)(ck + D + c0 + 2 * e), w2 = *(const f32x2*)(ck + 2 * D + c0 + 2 * e);
;                 const float lo = bflo(bq[hf][e]) * (w0[0] * (bflo(cp[hf][e]) * bflo(vp[hf][e])) + w1[0] * (bflo(cq[hf][e]) * bflo(vq[hf][e])) + w2[0] * (bflo(cn[hf][e]) * bflo(vn[hf][e])));
;                 const float hi = bfhi(bq[hf][e]) * (w0[1] * (bfhi(cp[hf][e]) * bfhi(vp[hf][e])) + w1[1] * (bfhi(cq[hf][e]) * bfhi(vq[hf][e])) + w2[1] * (bfhi(cn[hf][e]) * bfhi(vn[hf][e])));
;                 ow[e] = cvt_pk_bf16(lo, hi);
;             }
;             *(u32x4*)(H + (size_t)row * D + c0) = ow;
;         }
.Lcg8_nn4:
	v_lshlrev_b32_e32 v202, 16, v176
	v_and_b32_e32 v203, s14, v176
	v_pk_mul_f32 v[234:235], v[234:235], v[202:203]
	v_lshlrev_b32_e32 v206, 16, v177
	v_and_b32_e32 v207, s14, v177
	v_pk_mul_f32 v[236:237], v[236:237], v[206:207]
	v_lshlrev_b32_e32 v210, 16, v178
	v_and_b32_e32 v211, s14, v178
	v_pk_mul_f32 v[238:239], v[238:239], v[210:211]
	v_lshlrev_b32_e32 v202, 16, v179
	v_and_b32_e32 v203, s14, v179
	v_pk_mul_f32 v[240:241], v[240:241], v[202:203]
	v_lshlrev_b32_e32 v206, 16, v180
	v_and_b32_e32 v207, s14, v180
	v_pk_mul_f32 v[242:243], v[242:243], v[206:207]
	v_lshlrev_b32_e32 v210, 16, v181
	v_and_b32_e32 v211, s14, v181
	v_pk_mul_f32 v[244:245], v[244:245], v[210:211]
	v_lshlrev_b32_e32 v202, 16, v182
	v_and_b32_e32 v203, s14, v182
	v_pk_mul_f32 v[246:247], v[246:247], v[202:203]
	v_lshlrev_b32_e32 v206, 16, v183
	v_and_b32_e32 v207, s14, v183
	v_pk_mul_f32 v[248:249], v[248:249], v[206:207]
	v_cvt_pk_bf16_f32 v84, v234, v235
	v_cvt_pk_bf16_f32 v85, v236, v237
	v_cvt_pk_bf16_f32 v86, v238, v239
	v_cvt_pk_bf16_f32 v87, v240, v241
	v_cvt_pk_bf16_f32 v88, v242, v243
	v_cvt_pk_bf16_f32 v89, v244, v245
	v_cvt_pk_bf16_f32 v90, v246, v247
	v_cvt_pk_bf16_f32 v91, v248, v249
	global_store_dwordx4 v1, v[84:87], s[8:9]
	global_store_dwordx4 v1, v[88:91], s[8:9] offset:16
	s_add_u32 s8, s8, 0x800
	s_addc_u32 s9, s9, 0
	global_load_dwordx4 v[176:179], v1, s[6:7]
	global_load_dwordx4 v[180:183], v1, s[6:7] offset:16
	s_add_u32 s6, s6, 0x1800
	s_addc_u32 s7, s7, 0
	s_waitcnt vmcnt(16)
	v_lshlrev_b32_e32 v202, 16, v130
	v_and_b32_e32 v203, s14, v130
	v_lshlrev_b32_e32 v204, 16, v138
	v_and_b32_e32 v205, s14, v138
	v_pk_mul_f32 v[68:69], v[202:203], v[204:205]
	v_lshlrev_b32_e32 v206, 16, v131
	v_and_b32_e32 v207, s14, v131
	v_lshlrev_b32_e32 v208, 16, v139
	v_and_b32_e32 v209, s14, v139
	v_pk_mul_f32 v[70:71], v[206:207], v[208:209]
	v_lshlrev_b32_e32 v210, 16, v132
	v_and_b32_e32 v211, s14, v132
	v_lshlrev_b32_e32 v212, 16, v140
	v_and_b32_e32 v213, s14, v140
	v_pk_mul_f32 v[72:73], v[210:211], v[212:213]
	v_lshlrev_b32_e32 v202, 16, v133
	v_and_b32_e32 v203, s14, v133
	v_lshlrev_b32_e32 v204, 16, v141
	v_and_b32_e32 v205, s14, v141
	v_pk_mul_f32 v[74:75], v[202:203], v[204:205]
	v_lshlrev_b32_e32 v206, 16, v134
	v_and_b32_e32 v207, s14, v134
	v_lshlrev_b32_e32 v208, 16, v142
	v_and_b32_e32 v209, s14, v142
	v_pk_mul_f32 v[76:77], v[206:207], v[208:209]
	v_lshlrev_b32_e32 v210, 16, v135
	v_and_b32_e32 v211, s14, v135
	v_lshlrev_b32_e32 v212, 16, v143
	v_and_b32_e32 v213, s14, v143
	v_pk_mul_f32 v[78:79], v[210:211], v[212:213]
	v_lshlrev_b32_e32 v202, 16, v136
	v_and_b32_e32 v203, s14, v136
	v_lshlrev_b32_e32 v204, 16, v144
	v_and_b32_e32 v205, s14, v144
	v_pk_mul_f32 v[80:81], v[202:203], v[204:205]
	v_lshlrev_b32_e32 v206, 16, v137
	v_and_b32_e32 v207, s14, v137
	v_lshlrev_b32_e32 v208, 16, v145
	v_and_b32_e32 v209, s14, v145
	v_pk_mul_f32 v[82:83], v[206:207], v[208:209]
	s_add_i32 s12, s11, 5
	s_cmp_lt_u32 s12, 0x4000
	s_cselect_b32 s29, s3, s13
	s_and_b32 s27, s12, s29
	v_pk_mul_f32 v[234:235], v[20:21], v[52:53]
	v_pk_mul_f32 v[236:237], v[22:23], v[54:55]
	v_pk_mul_f32 v[238:239], v[24:25], v[56:57]
	v_pk_mul_f32 v[240:241], v[26:27], v[58:59]
	v_pk_mul_f32 v[242:243], v[28:29], v[60:61]
	v_pk_mul_f32 v[244:245], v[30:31], v[62:63]
	v_pk_mul_f32 v[246:247], v[32:33], v[64:65]
	v_pk_mul_f32 v[248:249], v[34:35], v[66:67]
	s_cmp_eq_u32 s27, 0
	s_cbranch_scc1 .Lcg8_np5
	v_pk_fma_f32 v[234:235], v[4:5], v[98:99], v[234:235]
	v_pk_fma_f32 v[236:237], v[6:7], v[100:101], v[236:237]
	v_pk_fma_f32 v[238:239], v[8:9], v[102:103], v[238:239]
	v_pk_fma_f32 v[240:241], v[10:11], v[104:105], v[240:241]
	v_pk_fma_f32 v[242:243], v[12:13], v[106:107], v[242:243]
	v_pk_fma_f32 v[244:245], v[14:15], v[108:109], v[244:245]
	v_pk_fma_f32 v[246:247], v[16:17], v[110:111], v[246:247]
	v_pk_fma_f32 v[248:249], v[18:19], v[112:113], v[248:249]

; __device__ __forceinline__ unsigned cvt_pk_bf16(float lo, float hi) { unsigned r; asm volatile("v_cvt_pk_bf16_f32 %0, %1, %2" : "=v"(r) : "v"(lo), "v"(hi)); return r; }
; __device__ __forceinline__ float bflo(unsigned w) { return __uint_as_float(w << 16); }
; __device__ __forceinline__ float bfhi(unsigned w) { return __uint_as_float(w & 0xffff0000u); }
; __device__ __forceinline__ void convgate_phase(const bf16_t* U, bf16_t* H, int rows, const float* ck, int gw, int NGW, int lane) {
;     ...
; #pragma unroll
;         for (int hf = 0; hf < 2; ++hf) {
;             const int c0 = lane * 16 + hf * 8;
;             u32x4 ow;
; #pragma unroll
;             for (int e = 0; e < 4; ++e) {
;                 const f32x2 w0 = *(const f32x2*)(ck + c0 + 2 * e), w1 = *(const f32x2*)(ck + D + c0 + 2 * e), w2 = *(const f32x2*)(ck + 2 * D + c0 + 2 * e);
;                 const float lo = bflo(bq[hf][e]) * (w0[0] * (bflo(cp[hf][e]) * bflo(vp[hf][e])) + w1[0] * (bflo(cq[hf][e]) * bflo(vq[hf][e])) + w2[0] * (bflo(cn[hf][e]) * bflo(vn[hf][e])));
;                 const float hi = bfhi(bq[hf][e]) * (w0[1] * (bfhi(cp[hf][e]) * bfhi(vp[hf][e])) + w1[1] * (bfhi(cq[hf][e]) * bfhi(vq[hf][e])) + w2[1] * (bfhi(cn[hf][e]) * bfhi(vn[hf][e])));
;                 ow[e] = cvt_pk_bf16(lo, hi);
;             }
;             *(u32x4*)(H + (size_t)row * D + c0) = ow;
;         }
.Lcg8_nn5:
	v_lshlrev_b32_e32 v202, 16, v226
	v_and_b32_e32 v203, s14, v226
	v_pk_mul_f32 v[234:235], v[234:235], v[202:203]
	v_lshlrev_b32_e32 v206, 16, v227
	v_and_b32_e32 v207, s14, v227
	v_pk_mul_f32 v[236:237], v[236:237], v[206:207]
	v_lshlrev_b32_e32 v210, 16, v228
	v_and_b32_e32 v211, s14, v228
	v_pk_mul_f32 v[238:239], v[238:239], v[210:211]
	v_lshlrev_b32_e32 v202, 16, v229
	v_and_b32_e32 v203, s14, v229
	v_pk_mul_f32 v[240:241], v[240:241], v[202:203]
	v_lshlrev_b32_e32 v206, 16, v230
	v_and_b32_e32 v207, s14, v230
	v_pk_mul_f32 v[242:243], v[242:243], v[206:207]
	v_lshlrev_b32_e32 v210, 16, v231
	v_and_b32_e32 v211, s14, v231
	v_pk_mul_f32 v[244:245], v[244:245], v[210:211]
	v_lshlrev_b32_e32 v202, 16, v232
	v_and_b32_e32 v203, s14, v232
	v_pk_mul_f32 v[246:247], v[246:247], v[202:203]
	v_lshlrev_b32_e32 v206, 16, v233
	v_and_b32_e32 v207, s14, v233
	v_pk_mul_f32 v[248:249], v[248:249], v[206:207]
	v_cvt_pk_bf16_f32 v84, v234, v235
	v_cvt_pk_bf16_f32 v85, v236, v237
	v_cvt_pk_bf16_f32 v86, v238, v239
	v_cvt_pk_bf16_f32 v87, v240, v241
	v_cvt_pk_bf16_f32 v88, v242, v243
	v_cvt_pk_bf16_f32 v89, v244, v245
	v_cvt_pk_bf16_f32 v90, v246, v247
	v_cvt_pk_bf16_f32 v91, v248, v249
	global_store_dwordx4 v1, v[84:87], s[8:9]
	global_store_dwordx4 v1, v[88:91], s[8:9] offset:16
	s_add_u32 s8, s8, 0x800
	s_addc_u32 s9, s9, 0
	s_waitcnt vmcnt(10)
	v_lshlrev_b32_e32 v202, 16, v160
	v_and_b32_e32 v203, s14, v160
	v_lshlrev_b32_e32 v204, 16, v168
	v_and_b32_e32 v205, s14, v168
	v_pk_mul_f32 v[98:99], v[202:203], v[204:205]
	v_lshlrev_b32_e32 v206, 16, v161
	v_and_b32_e32 v207, s14, v161
	v_lshlrev_b32_e32 v208, 16, v169
	v_and_b32_e32 v209, s14, v169
	v_pk_mul_f32 v[100:101], v[206:207], v[208:209]
	v_lshlrev_b32_e32 v210, 16, v162
	v_and_b32_e32 v211, s14, v162
	v_lshlrev_b32_e32 v212, 16, v170
	v_and_b32_e32 v213, s14, v170
	v_pk_mul_f32 v[102:103], v[210:211], v[212:213]
	v_lshlrev_b32_e32 v202, 16, v163
	v_and_b32_e32 v203, s14, v163
	v_lshlrev_b32_e32 v204, 16, v171
	v_and_b32_e32 v205, s14, v171
	v_pk_mul_f32 v[104:105], v[202:203], v[204:205]
	v_lshlrev_b32_e32 v206, 16, v164
	v_and_b32_e32 v207, s14, v164
	v_lshlrev_b32_e32 v208, 16, v172
	v_and_b32_e32 v209, s14, v172
	v_pk_mul_f32 v[106:107], v[206:207], v[208:209]
	v_lshlrev_b32_e32 v210, 16, v165
	v_and_b32_e32 v211, s14, v165
	v_lshlrev_b32_e32 v212, 16, v173
	v_and_b32_e32 v213, s14, v173
	v_pk_mul_f32 v[108:109], v[210:211], v[212:213]
	v_lshlrev_b32_e32 v202, 16, v166
	v_and_b32_e32 v203, s14, v166
	v_lshlrev_b32_e32 v204, 16, v174
	v_and_b32_e32 v205, s14, v174
	v_pk_mul_f32 v[110:111], v[202:203], v[204:205]
	v_lshlrev_b32_e32 v206, 16, v167
	v_and_b32_e32 v207, s14, v167
	v_lshlrev_b32_e32 v208, 16, v175
	v_and_b32_e32 v209, s14, v175
	v_pk_mul_f32 v[112:113], v[206:207], v[208:209]
	s_add_i32 s12, s11, 6
	s_cmp_lt_u32 s12, 0x4000
	s_cselect_b32 s29, s3, s13
	s_and_b32 s27, s12, s29
	v_pk_mul_f32 v[234:235], v[20:21], v[68:69]
	v_pk_mul_f32 v[236:237], v[22:23], v[70:71]
	v_pk_mul_f32 v[238:239], v[24:25], v[72:73]
	v_pk_mul_f32 v[240:241], v[26:27], v[74:75]
	v_pk_mul_f32 v[242:243], v[28:29], v[76:77]
	v_pk_mul_f32 v[244:245], v[30:31], v[78:79]
	v_pk_mul_f32 v[246:247], v[32:33], v[80:81]
	v_pk_mul_f32 v[248:249], v[34:35], v[82:83]
	s_cmp_eq_u32 s27, 0
	s_cbranch_scc1 .Lcg8_np6
	v_pk_fma_f32 v[234:235], v[4:5], v[52:53], v[234:235]
	v_pk_fma_f32 v[236:237], v[6:7], v[54:55], v[236:237]
	v_pk_fma_f32 v[238:239], v[8:9], v[56:57], v[238:239]
	v_pk_fma_f32 v[240:241], v[10:11], v[58:59], v[240:241]
	v_pk_fma_f32 v[242:243], v[12:13], v[60:61], v[242:243]
	v_pk_fma_f32 v[244:245], v[14:15], v[62:63], v[244:245]
	v_pk_fma_f32 v[246:247], v[16:17], v[64:65], v[246:247]
	v_pk_fma_f32 v[248:249], v[18:19], v[66:67], v[248:249]

; __device__ __forceinline__ unsigned cvt_pk_bf16(float lo, float hi) { unsigned r; asm volatile("v_cvt_pk_bf16_f32 %0, %1, %2" : "=v"(r) : "v"(lo), "v"(hi)); return r; }
; __device__ __forceinline__ float bflo(unsigned w) { return __uint_as_float(w << 16); }
; __device__ __forceinline__ float bfhi(unsigned w) { return __uint_as_float(w & 0xffff0000u); }
; __device__ __forceinline__ void convgate_phase(const bf16_t* U, bf16_t* H, int rows, const float* ck, int gw, int NGW, int lane) {
;     ...
; #pragma unroll
;         for (int hf = 0; hf < 2; ++hf) {
;             const int c0 = lane * 16 + hf * 8;
;             u32x4 ow;
; #pragma unroll
;             for (int e = 0; e < 4; ++e) {
;                 const f32x2 w0 = *(const f32x2*)(ck + c0 + 2 * e), w1 = *(const f32x2*)(ck + D + c0 + 2 * e), w2 = *(const f32x2*)(ck + 2 * D + c0 + 2 * e);
;                 const float lo = bflo(bq[hf][e]) * (w0[0] * (bflo(cp[hf][e]) * bflo(vp[hf][e])) + w1[0] * (bflo(cq[hf][e]) * bflo(vq[hf][e])) + w2[0] * (bflo(cn[hf][e]) * bflo(vn[hf][e])));
;                 const float hi = bfhi(bq[hf][e]) * (w0[1] * (bfhi(cp[hf][e]) * bfhi(vp[hf][e])) + w1[1] * (bfhi(cq[hf][e]) * bfhi(vq[hf][e])) + w2[1] * (bfhi(cn[hf][e]) * bfhi(vn[hf][e])));
;                 ow[e] = cvt_pk_bf16(lo, hi);
;             }
;             *(u32x4*)(H + (size_t)row * D + c0) = ow;
;         }
.Lcg8_nn6:
	v_lshlrev_b32_e32 v202, 16, v146
	v_and_b32_e32 v203, s14, v146
	v_pk_mul_f32 v[234:235], v[234:235], v[202:203]
	v_lshlrev_b32_e32 v206, 16, v147
	v_and_b32_e32 v207, s14, v147
	v_pk_mul_f32 v[236:237], v[236:237], v[206:207]
	v_lshlrev_b32_e32 v210, 16, v148
	v_and_b32_e32 v211, s14, v148
	v_pk_mul_f32 v[238:239], v[238:239], v[210:211]
	v_lshlrev_b32_e32 v202, 16, v149
	v_and_b32_e32 v203, s14, v149
	v_pk_mul_f32 v[240:241], v[240:241], v[202:203]
	v_lshlrev_b32_e32 v206, 16, v150
	v_and_b32_e32 v207, s14, v150
	v_pk_mul_f32 v[242:243], v[242:243], v[206:207]
	v_lshlrev_b32_e32 v210, 16, v151
	v_and_b32_e32 v211, s14, v151
	v_pk_mul_f32 v[244:245], v[244:245], v[210:211]
	v_lshlrev_b32_e32 v202, 16, v152
	v_and_b32_e32 v203, s14, v152
	v_pk_mul_f32 v[246:247], v[246:247], v[202:203]
	v_lshlrev_b32_e32 v206, 16, v153
	v_and_b32_e32 v207, s14, v153
	v_pk_mul_f32 v[248:249], v[248:249], v[206:207]
	v_cvt_pk_bf16_f32 v84, v234, v235
	v_cvt_pk_bf16_f32 v85, v236, v237
	v_cvt_pk_bf16_f32 v86, v238, v239
	v_cvt_pk_bf16_f32 v87, v240, v241
	v_cvt_pk_bf16_f32 v88, v242, v243
	v_cvt_pk_bf16_f32 v89, v244, v245
	v_cvt_pk_bf16_f32 v90, v246, v247
	v_cvt_pk_bf16_f32 v91, v248, v249
	global_store_dwordx4 v1, v[84:87], s[8:9]
	global_store_dwordx4 v1, v[88:91], s[8:9] offset:16
	s_add_u32 s8, s8, 0x800
	s_addc_u32 s9, s9, 0
	s_waitcnt vmcnt(4)
	v_lshlrev_b32_e32 v202, 16, v114
	v_and_b32_e32 v203, s14, v114
	v_lshlrev_b32_e32 v204, 16, v122
	v_and_b32_e32 v205, s14, v122
	v_pk_mul_f32 v[52:53], v[202:203], v[204:205]
	v_lshlrev_b32_e32 v206, 16, v115
	v_and_b32_e32 v207, s14, v115
	v_lshlrev_b32_e32 v208, 16, v123
	v_and_b32_e32 v209, s14, v123
	v_pk_mul_f32 v[54:55], v[206:207], v[208:209]
	v_lshlrev_b32_e32 v210, 16, v116
	v_and_b32_e32 v211, s14, v116
	v_lshlrev_b32_e32 v212, 16, v124
	v_and_b32_e32 v213, s14, v124
	v_pk_mul_f32 v[56:57], v[210:211], v[212:213]
	v_lshlrev_b32_e32 v202, 16, v117
	v_and_b32_e32 v203, s14, v117
	v_lshlrev_b32_e32 v204, 16, v125
	v_and_b32_e32 v205, s14, v125
	v_pk_mul_f32 v[58:59], v[202:203], v[204:205]
	v_lshlrev_b32_e32 v206, 16, v118
	v_and_b32_e32 v207, s14, v118
	v_lshlrev_b32_e32 v208, 16, v126
	v_and_b32_e32 v209, s14, v126
	v_pk_mul_f32 v[60:61], v[206:207], v[208:209]
	v_lshlrev_b32_e32 v210, 16, v119
	v_and_b32_e32 v211, s14, v119
	v_lshlrev_b32_e32 v212, 16, v127
	v_and_b32_e32 v213, s14, v127
	v_pk_mul_f32 v[62:63], v[210:211], v[212:213]
	v_lshlrev_b32_e32 v202, 16, v120
	v_and_b32_e32 v203, s14, v120
	v_lshlrev_b32_e32 v204, 16, v128
	v_and_b32_e32 v205, s14, v128
	v_pk_mul_f32 v[64:65], v[202:203], v[204:205]
	v_lshlrev_b32_e32 v206, 16, v121
	v_and_b32_e32 v207, s14, v121
	v_lshlrev_b32_e32 v208, 16, v129
	v_and_b32_e32 v209, s14, v129
	v_pk_mul_f32 v[66:67], v[206:207], v[208:209]
	s_add_i32 s12, s11, 7
	s_cmp_lt_u32 s12, 0x4000
	s_cselect_b32 s29, s3, s13
	s_and_b32 s27, s12, s29
	v_pk_mul_f32 v[234:235], v[20:21], v[98:99]
	v_pk_mul_f32 v[236:237], v[22:23], v[100:101]
	v_pk_mul_f32 v[238:239], v[24:25], v[102:103]
	v_pk_mul_f32 v[240:241], v[26:27], v[104:105]
	v_pk_mul_f32 v[242:243], v[28:29], v[106:107]
	v_pk_mul_f32 v[244:245], v[30:31], v[108:109]
	v_pk_mul_f32 v[246:247], v[32:33], v[110:111]
	v_pk_mul_f32 v[248:249], v[34:35], v[112:113]
	s_cmp_eq_u32 s27, 0
	s_cbranch_scc1 .Lcg8_np7
	v_pk_fma_f32 v[234:235], v[4:5], v[68:69], v[234:235]
	v_pk_fma_f32 v[236:237], v[6:7], v[70:71], v[236:237]
	v_pk_fma_f32 v[238:239], v[8:9], v[72:73], v[238:239]
	v_pk_fma_f32 v[240:241], v[10:11], v[74:75], v[240:241]
	v_pk_fma_f32 v[242:243], v[12:13], v[76:77], v[242:243]
	v_pk_fma_f32 v[244:245], v[14:15], v[78:79], v[244:245]
	v_pk_fma_f32 v[246:247], v[16:17], v[80:81], v[246:247]
	v_pk_fma_f32 v[248:249], v[18:19], v[82:83], v[248:249]

; __device__ __forceinline__ unsigned cvt_pk_bf16(float lo, float hi) { unsigned r; asm volatile("v_cvt_pk_bf16_f32 %0, %1, %2" : "=v"(r) : "v"(lo), "v"(hi)); return r; }
; __device__ __forceinline__ float bflo(unsigned w) { return __uint_as_float(w << 16); }
; __device__ __forceinline__ float bfhi(unsigned w) { return __uint_as_float(w & 0xffff0000u); }
; __device__ __forceinline__ void convgate_phase(const bf16_t* U, bf16_t* H, int rows, const float* ck, int gw, int NGW, int lane) {
;     ...
;         for (int hf = 0; hf < 2; ++hf) {
;             const int c0 = lane * 16 + hf * 8;
;             u32x4 ow;
; #pragma unroll
;             for (int e = 0; e < 4; ++e) {
;                 const f32x2 w0 = *(const f32x2*)(ck + c0 + 2 * e), w1 = *(const f32x2*)(ck + D + c0 + 2 * e), w2 = *(const f32x2*)(ck + 2 * D + c0 + 2 * e);
;                 const float lo = bflo(bq[hf][e]) * (w0[0] * (bflo(cp[hf][e]) * bflo(vp[hf][e])) + w1[0] * (bflo(cq[hf][e]) * bflo(vq[hf][e])) + w2[0] * (bflo(cn[hf][e]) * bflo(vn[hf][e])));
;                 const float hi = bfhi(bq[hf][e]) * (w0[1] * (bfhi(cp[hf][e]) * bfhi(vp[hf][e])) + w1[1] * (bfhi(cq[hf][e]) * bfhi(vq[hf][e])) + w2[1] * (bfhi(cn[hf][e]) * bfhi(vn[hf][e])));
;                 ow[e] = cvt_pk_bf16(lo, hi);
;             }
;             *(u32x4*)(H + (size_t)row * D + c0) = ow;
;         }
.Lcg8_nn7:
	v_lshlrev_b32_e32 v202, 16, v176
	v_and_b32_e32 v203, s14, v176
	v_pk_mul_f32 v[234:235], v[234:235], v[202:203]
	v_lshlrev_b32_e32 v206, 16, v177
	v_and_b32_e32 v207, s14, v177
	v_pk_mul_f32 v[236:237], v[236:237], v[206:207]
	v_lshlrev_b32_e32 v210, 16, v178
	v_and_b32_e32 v211, s14, v178
	v_pk_mul_f32 v[238:239], v[238:239], v[210:211]
	v_lshlrev_b32_e32 v202, 16, v179
	v_and_b32_e32 v203, s14, v179
	v_pk_mul_f32 v[240:241], v[240:241], v[202:203]
	v_lshlrev_b32_e32 v206, 16, v180
	v_and_b32_e32 v207, s14, v180
	v_pk_mul_f32 v[242:243], v[242:243], v[206:207]
	v_lshlrev_b32_e32 v210, 16, v181
	v_and_b32_e32 v211, s14, v181
	v_pk_mul_f32 v[244:245], v[244:245], v[210:211]
	v_lshlrev_b32_e32 v202, 16, v182
	v_and_b32_e32 v203, s14, v182
	v_pk_mul_f32 v[246:247], v[246:247], v[202:203]
	v_lshlrev_b32_e32 v206, 16, v183
	v_and_b32_e32 v207, s14, v183
	v_pk_mul_f32 v[248:249], v[248:249], v[206:207]
	v_cvt_pk_bf16_f32 v84, v234, v235
	v_cvt_pk_bf16_f32 v85, v236, v237
	v_cvt_pk_bf16_f32 v86, v238, v239
	v_cvt_pk_bf16_f32 v87, v240, v241
	v_cvt_pk_bf16_f32 v88, v242, v243
	v_cvt_pk_bf16_f32 v89, v244, v245
	v_cvt_pk_bf16_f32 v90, v246, v247
	v_cvt_pk_bf16_f32 v91, v248, v249
	global_store_dwordx4 v1, v[84:87], s[8:9]
	global_store_dwordx4 v1, v[88:91], s[8:9] offset:16
	s_add_u32 s8, s8, 0x800
	s_addc_u32 s9, s9, 0
	s_branch .Lcg_done
.Lcg_done:
	s_ashr_i32 s17, s16, 31
.LBB0_906:
	v_writelane_b32 v254, s16, 28
	s_nop 1
	v_writelane_b32 v254, s17, 29
